# in-proj GEMM epilogue: 320 packed f32 ops (v_pk_mul/v_pk_fma) split into scalar f32 ops, bit-identical
# speedup vs baseline: 1.0288x; 1.0288x over previous
; __device__ __forceinline__ unsigned pk2(float lo, float hi) { f32x2v v = {lo, hi}; bf16x2_t b = __builtin_convertvector(v, bf16x2_t); return __builtin_bit_cast(unsigned, b); }
;     __device__ __forceinline__ void operator()(const pg8::f32x4 (&acc)[2][2][4][2], const pg8::Unit& u, int wr, int wc, int fr, int fq) const {
;     ...
;                 const int row = row0 + ai * 128 + m * 16;
;                 const int tok = row & (SEQ - 1);
;                 bf16_t* rowp = base + (size_t)((row >> 13) * LP + PADF + NMETA + tok) * ldc + col0;
;                 const float scr = sc * rstd[row];
;                 f32x4 c0 = {1.f, 1.f, 1.f, 1.f}, c1 = c0, s0 = {0.f, 0.f, 0.f, 0.f}, s1 = s0;
;                 if (dorope) {
;                     const int pos = NMETA + tok;
;                     if (fq < 2) { c0 = *(const f32x4*)(ropec + pos * 8); c1 = *(const f32x4*)(ropec + pos * 8 + 4); s0 = *(const f32x4*)(ropes + pos * 8); s1 = *(const f32x4*)(ropes + pos * 8 + 4); }
;                 }
; #pragma unroll
;                 for (int bj = 0; bj < 2; ++bj) {
;                     f32x4 v0 = acc[ai][bj][m][0] * scr, v1 = acc[ai][bj][m][1] * scr;
;                     if (dorope) {
;                         f32x4 p0, p1;
; #pragma unroll
;                         for (int e = 0; e < 4; ++e) { p0[e] = __shfl_xor(v0[e], 16); p1[e] = __shfl_xor(v1[e], 16); }
;                         v0 = v0 * c0 + (p0 * s0) * sgn; v1 = v1 * c1 + (p1 * s1) * sgn;
;                     }
;                     if (silu) {
; #pragma unroll
;                         for (int e = 0; e < 4; ++e) { v0[e] = v0[e] * __builtin_amdgcn_rcpf(1.f + __builtin_amdgcn_exp2f(-LOG2E * v0[e])); v1[e] = v1[e] * __builtin_amdgcn_rcpf(1.f + __builtin_amdgcn_exp2f(-LOG2E * v1[e])); }
;                     }
;                     u32x4 w; w.x = pk2(v0[0], v0[1]); w.y = pk2(v0[2], v0[3]); w.z = pk2(v1[0], v1[1]); w.w = pk2(v1[2], v1[3]);
;                     *(u32x4*)(rowp + bj * 128) = w;
.LBB0_337:
	s_or_b64 exec, exec, s[28:29]
	s_waitcnt vmcnt(0)
	v_mul_f32_e32 v170, s19, v165
	v_cndmask_b32_e64 v165, 0, 1, s[24:25]
	v_mul_f32_e32 v132, v132, v170
	v_mul_f32_e32 v133, v133, v170
	v_mul_f32_e32 v130, v130, v170
	v_mul_f32_e32 v131, v131, v170
	v_mul_f32_e32 v128, v128, v170
	v_mul_f32_e32 v129, v129, v170
	v_cmp_ne_u32_e64 s[46:47], 1, v165
	s_andn2_b64 vcc, exec, s[24:25]
	v_mul_f32_e32 v172, v126, v170
	v_mul_f32_e32 v173, v127, v170
	s_cbranch_vccnz .LBB0_339
	v_and_b32_e32 v127, 64, v218
	v_xor_b32_e32 v126, 16, v218
	v_add_u32_e32 v127, 64, v127
	v_cmp_lt_i32_e32 vcc, v126, v127
	s_nop 1
	v_cndmask_b32_e32 v126, v218, v126, vcc
	v_lshlrev_b32_e32 v165, 2, v126
	ds_bpermute_b32 v126, v165, v130
	ds_bpermute_b32 v127, v165, v131
	ds_bpermute_b32 v168, v165, v172
	ds_bpermute_b32 v176, v165, v132
	ds_bpermute_b32 v177, v165, v133
	ds_bpermute_b32 v169, v165, v173
	ds_bpermute_b32 v178, v165, v128
	ds_bpermute_b32 v179, v165, v129
	s_waitcnt lgkmcnt(6)
	v_mul_f32_e32 v126, v146, v126
	v_mul_f32_e32 v127, v147, v127
	s_waitcnt lgkmcnt(3)
	v_mul_f32_e32 v176, v148, v176
	v_mul_f32_e32 v177, v149, v177
	v_mul_f32_e32 v126, v156, v126
	v_mul_f32_e32 v127, v157, v127
	s_waitcnt lgkmcnt(2)
	v_mul_f32_e32 v168, v142, v168
	v_mul_f32_e32 v169, v143, v169
	v_fma_f32 v130, v130, v138, v126
	v_fma_f32 v131, v131, v139, v127
	s_waitcnt lgkmcnt(0)
	v_mul_f32_e32 v126, v144, v178
	v_mul_f32_e32 v127, v145, v179
	v_mul_f32_e32 v176, v158, v176
	v_mul_f32_e32 v177, v159, v177
	v_mul_f32_e32 v168, v156, v168
	v_mul_f32_e32 v169, v157, v169
	v_mul_f32_e32 v126, v158, v126
	v_mul_f32_e32 v127, v159, v127
	v_fma_f32 v132, v132, v140, v176
	v_fma_f32 v133, v133, v141, v177
	v_fma_f32 v128, v128, v136, v126
	v_fma_f32 v129, v129, v137, v127
	v_fma_f32 v172, v172, v134, v168
	v_fma_f32 v173, v173, v135, v169
.LBB0_339:
	v_cndmask_b32_e64 v126, 0, 1, s[54:55]
	v_cmp_ne_u32_e64 s[48:49], 1, v126
	s_andn2_b64 vcc, exec, s[54:55]
	s_cbranch_vccnz .LBB0_341
	v_mul_f32_e32 v165, 0xbfb8aa3b, v173
	v_exp_f32_e32 v165, v165
	v_mul_f32_e32 v127, 0xbfb8aa3b, v172
	v_exp_f32_e32 v127, v127
	v_mul_f32_e32 v126, 0xbfb8aa3b, v130
	v_add_f32_e32 v165, 1.0, v165
	v_rcp_f32_e32 v169, v165
	v_mul_f32_e32 v165, 0xbfb8aa3b, v132
	v_add_f32_e32 v127, 1.0, v127
	v_exp_f32_e32 v165, v165
	v_rcp_f32_e32 v168, v127
	v_mul_f32_e32 v127, 0xbfb8aa3b, v131
	v_exp_f32_e32 v126, v126
	v_exp_f32_e32 v127, v127
	v_add_f32_e32 v165, 1.0, v165
	v_rcp_f32_e32 v176, v165
	v_mul_f32_e32 v165, 0xbfb8aa3b, v128
	v_add_f32_e32 v126, 1.0, v126
	v_add_f32_e32 v127, 1.0, v127
	v_exp_f32_e32 v165, v165
	v_rcp_f32_e32 v126, v126
	v_rcp_f32_e32 v127, v127
	v_mul_f32_e32 v172, v172, v168
	v_mul_f32_e32 v173, v173, v169
	v_add_f32_e32 v165, 1.0, v165
	v_rcp_f32_e32 v178, v165
	v_mul_f32_e32 v165, 0xbfb8aa3b, v133
	v_mul_f32_e32 v130, v130, v126
	v_mul_f32_e32 v131, v131, v127
	v_mul_f32_e32 v126, 0xbfb8aa3b, v129
	v_exp_f32_e32 v165, v165
	v_exp_f32_e32 v126, v126
	v_add_f32_e32 v165, 1.0, v165
	v_add_f32_e32 v126, 1.0, v126
	v_rcp_f32_e32 v177, v165
	v_rcp_f32_e32 v179, v126
	v_mul_f32_e32 v132, v132, v176
	v_mul_f32_e32 v133, v133, v177
	v_mul_f32_e32 v128, v128, v178
	v_mul_f32_e32 v129, v129, v179
.LBB0_341:
	s_lshl_b32 s0, s0, 9
	s_add_u32 s0, s20, s0
	s_addc_u32 s1, s21, 0
	v_mov_b32_e32 v165, v0
	v_lshl_add_u64 v[168:169], s[0:1], 0, v[164:165]
	v_ashrrev_i32_e32 v126, 13, v166
	s_movk_i32 s0, 0x2080
	v_mad_i32_i24 v165, v126, s0, v221
	v_add_u32_e32 v126, v165, v167
	v_ashrrev_i32_e32 v127, 31, v126
	v_mul_lo_u32 v167, s2, v127
	v_mul_lo_u32 v175, s3, v126
	v_mad_u64_u32 v[126:127], s[0:1], s2, v126, 0
	v_mov_b32_e32 v171, v170
	v_add3_u32 v127, v127, v167, v175
	v_cvt_pk_bf16_f32 v130, v130, v131
	v_cvt_pk_bf16_f32 v131, v132, v133
	v_cvt_pk_bf16_f32 v133, v128, v129
	v_mov_b32_e32 v128, v170
	v_mov_b32_e32 v129, v170
	v_lshl_add_u64 v[126:127], v[126:127], 1, v[168:169]
	v_cvt_pk_bf16_f32 v132, v172, v173
	v_mul_f32_e32 v124, v124, v128
	v_mul_f32_e32 v125, v125, v129
	v_mul_f32_e32 v122, v122, v170
	v_mul_f32_e32 v123, v123, v171
	v_mul_f32_e32 v120, v120, v128
	v_mul_f32_e32 v121, v121, v129
	s_and_b64 vcc, exec, s[46:47]
	v_mul_f32_e32 v118, v118, v170
	v_mul_f32_e32 v119, v119, v171
	global_store_dwordx4 v[126:127], v[130:133], off
	s_cbranch_vccnz .LBB0_343
	v_and_b32_e32 v129, 64, v218
	v_xor_b32_e32 v128, 16, v218
	v_add_u32_e32 v129, 64, v129
	v_cmp_lt_i32_e32 vcc, v128, v129
	s_nop 1
	v_cndmask_b32_e32 v128, v218, v128, vcc
	v_lshlrev_b32_e32 v167, 2, v128
	ds_bpermute_b32 v128, v167, v122
	ds_bpermute_b32 v129, v167, v123
	ds_bpermute_b32 v130, v167, v118
	ds_bpermute_b32 v132, v167, v124
	ds_bpermute_b32 v133, v167, v125
	ds_bpermute_b32 v131, v167, v119
	ds_bpermute_b32 v170, v167, v120
	ds_bpermute_b32 v171, v167, v121
	s_waitcnt lgkmcnt(6)
	v_mul_f32_e32 v128, v146, v128
	v_mul_f32_e32 v129, v147, v129
	s_waitcnt lgkmcnt(3)
	v_mul_f32_e32 v132, v148, v132
	v_mul_f32_e32 v133, v149, v133
	v_mul_f32_e32 v128, v156, v128
	v_mul_f32_e32 v129, v157, v129
	s_waitcnt lgkmcnt(2)
	v_mul_f32_e32 v130, v142, v130
	v_mul_f32_e32 v131, v143, v131
	v_fma_f32 v122, v122, v138, v128
	v_fma_f32 v123, v123, v139, v129
	s_waitcnt lgkmcnt(0)
	v_mul_f32_e32 v128, v144, v170
	v_mul_f32_e32 v129, v145, v171
	v_mul_f32_e32 v132, v158, v132
	v_mul_f32_e32 v133, v159, v133
	v_mul_f32_e32 v130, v156, v130
	v_mul_f32_e32 v131, v157, v131
	v_mul_f32_e32 v128, v158, v128
	v_mul_f32_e32 v129, v159, v129
	v_fma_f32 v124, v124, v140, v132
	v_fma_f32 v125, v125, v141, v133
	v_fma_f32 v120, v120, v136, v128
	v_fma_f32 v121, v121, v137, v129
	v_fma_f32 v118, v118, v134, v130
	v_fma_f32 v119, v119, v135, v131
.LBB0_343:
	s_and_b64 vcc, exec, s[48:49]
	s_cbranch_vccnz .LBB0_345
	v_mul_f32_e32 v129, 0xbfb8aa3b, v118
	v_exp_f32_e32 v129, v129
	v_mul_f32_e32 v128, 0xbfb8aa3b, v122
	v_exp_f32_e32 v128, v128
	v_mul_f32_e32 v133, 0xbfb8aa3b, v120
	v_add_f32_e32 v129, 1.0, v129
	v_rcp_f32_e32 v130, v129
	v_mul_f32_e32 v129, 0xbfb8aa3b, v123
	v_exp_f32_e32 v129, v129
	v_add_f32_e32 v128, 1.0, v128
	v_exp_f32_e32 v133, v133
	v_rcp_f32_e32 v128, v128
	v_add_f32_e32 v129, 1.0, v129
	v_rcp_f32_e32 v129, v129
	v_add_f32_e32 v133, 1.0, v133
	v_mul_f32_e32 v131, 0xbfb8aa3b, v119
	v_mul_f32_e32 v132, 0xbfb8aa3b, v124
	v_rcp_f32_e32 v134, v133
	v_mul_f32_e32 v133, 0xbfb8aa3b, v125
	v_mul_f32_e32 v122, v122, v128
	v_mul_f32_e32 v123, v123, v129
	v_mul_f32_e32 v128, 0xbfb8aa3b, v121
	v_exp_f32_e32 v131, v131
	v_exp_f32_e32 v132, v132
	v_exp_f32_e32 v133, v133
	v_exp_f32_e32 v128, v128
	v_add_f32_e32 v131, 1.0, v131
	v_add_f32_e32 v132, 1.0, v132
	v_add_f32_e32 v133, 1.0, v133
	v_add_f32_e32 v128, 1.0, v128
	v_rcp_f32_e32 v131, v131
	v_rcp_f32_e32 v132, v132
	v_rcp_f32_e32 v133, v133
	v_rcp_f32_e32 v135, v128
	v_mul_f32_e32 v118, v118, v130
	v_mul_f32_e32 v119, v119, v131
	v_mul_f32_e32 v124, v124, v132
	v_mul_f32_e32 v125, v125, v133
	v_mul_f32_e32 v120, v120, v134
	v_mul_f32_e32 v121, v121, v135

; __device__ __forceinline__ unsigned pk2(float lo, float hi) { f32x2v v = {lo, hi}; bf16x2_t b = __builtin_convertvector(v, bf16x2_t); return __builtin_bit_cast(unsigned, b); }
;     __device__ __forceinline__ void operator()(const pg8::f32x4 (&acc)[2][2][4][2], const pg8::Unit& u, int wr, int wc, int fr, int fq) const {
;     ...
;                 const int row = row0 + ai * 128 + m * 16;
;                 const int tok = row & (SEQ - 1);
;                 bf16_t* rowp = base + (size_t)((row >> 13) * LP + PADF + NMETA + tok) * ldc + col0;
;                 const float scr = sc * rstd[row];
;                 f32x4 c0 = {1.f, 1.f, 1.f, 1.f}, c1 = c0, s0 = {0.f, 0.f, 0.f, 0.f}, s1 = s0;
;                 if (dorope) {
;                     const int pos = NMETA + tok;
;                     if (fq < 2) { c0 = *(const f32x4*)(ropec + pos * 8); c1 = *(const f32x4*)(ropec + pos * 8 + 4); s0 = *(const f32x4*)(ropes + pos * 8); s1 = *(const f32x4*)(ropes + pos * 8 + 4); }
;                 }
; #pragma unroll
;                 for (int bj = 0; bj < 2; ++bj) {
;                     f32x4 v0 = acc[ai][bj][m][0] * scr, v1 = acc[ai][bj][m][1] * scr;
;                     if (dorope) {
;                         f32x4 p0, p1;
; #pragma unroll
;                         for (int e = 0; e < 4; ++e) { p0[e] = __shfl_xor(v0[e], 16); p1[e] = __shfl_xor(v1[e], 16); }
;                         v0 = v0 * c0 + (p0 * s0) * sgn; v1 = v1 * c1 + (p1 * s1) * sgn;
;                     }
;                     if (silu) {
; #pragma unroll
;                         for (int e = 0; e < 4; ++e) { v0[e] = v0[e] * __builtin_amdgcn_rcpf(1.f + __builtin_amdgcn_exp2f(-LOG2E * v0[e])); v1[e] = v1[e] * __builtin_amdgcn_rcpf(1.f + __builtin_amdgcn_exp2f(-LOG2E * v1[e])); }
;                     }
;                     u32x4 w; w.x = pk2(v0[0], v0[1]); w.y = pk2(v0[2], v0[3]); w.z = pk2(v1[0], v1[1]); w.w = pk2(v1[2], v1[3]);
;                     *(u32x4*)(rowp + bj * 128) = w;
.LBB0_347:
	s_or_b64 exec, exec, s[20:21]
	v_mul_f32_e32 v134, s19, v134
	v_mul_f32_e32 v116, v116, v134
	v_mul_f32_e32 v117, v117, v134
	v_mul_f32_e32 v114, v114, v134
	v_mul_f32_e32 v115, v115, v134
	v_mul_f32_e32 v112, v112, v134
	v_mul_f32_e32 v113, v113, v134
	s_and_b64 vcc, exec, s[46:47]
	v_mul_f32_e32 v136, v110, v134
	v_mul_f32_e32 v137, v111, v134
	s_cbranch_vccnz .LBB0_349
	v_and_b32_e32 v111, 64, v218
	v_xor_b32_e32 v110, 16, v218
	v_add_u32_e32 v111, 64, v111
	v_cmp_lt_i32_e32 vcc, v110, v111
	s_nop 1
	v_cndmask_b32_e32 v110, v218, v110, vcc
	v_lshlrev_b32_e32 v135, 2, v110
	ds_bpermute_b32 v110, v135, v114
	ds_bpermute_b32 v111, v135, v115
	ds_bpermute_b32 v140, v135, v136
	ds_bpermute_b32 v142, v135, v116
	ds_bpermute_b32 v143, v135, v117
	ds_bpermute_b32 v141, v135, v137
	ds_bpermute_b32 v144, v135, v112
	ds_bpermute_b32 v145, v135, v113
	s_waitcnt lgkmcnt(6)
	v_mul_f32_e32 v110, v130, v110
	v_mul_f32_e32 v111, v131, v111
	s_waitcnt lgkmcnt(3)
	v_mul_f32_e32 v142, v132, v142
	v_mul_f32_e32 v143, v133, v143
	v_mul_f32_e32 v110, v156, v110
	v_mul_f32_e32 v111, v157, v111
	s_waitcnt lgkmcnt(2)
	v_mul_f32_e32 v140, v126, v140
	v_mul_f32_e32 v141, v127, v141
	v_fma_f32 v114, v114, v122, v110
	v_fma_f32 v115, v115, v123, v111
	s_waitcnt lgkmcnt(0)
	v_mul_f32_e32 v110, v128, v144
	v_mul_f32_e32 v111, v129, v145
	v_mul_f32_e32 v142, v158, v142
	v_mul_f32_e32 v143, v159, v143
	v_mul_f32_e32 v140, v156, v140
	v_mul_f32_e32 v141, v157, v141
	v_mul_f32_e32 v110, v158, v110
	v_mul_f32_e32 v111, v159, v111
	v_fma_f32 v116, v116, v124, v142
	v_fma_f32 v117, v117, v125, v143
	v_fma_f32 v112, v112, v120, v110
	v_fma_f32 v113, v113, v121, v111
	v_fma_f32 v136, v136, v118, v140
	v_fma_f32 v137, v137, v119, v141
.LBB0_349:
	s_and_b64 vcc, exec, s[48:49]
	s_cbranch_vccnz .LBB0_351
	v_mul_f32_e32 v135, 0xbfb8aa3b, v137
	v_exp_f32_e32 v135, v135
	v_mul_f32_e32 v111, 0xbfb8aa3b, v136
	v_exp_f32_e32 v111, v111
	v_mul_f32_e32 v110, 0xbfb8aa3b, v114
	v_add_f32_e32 v135, 1.0, v135
	v_rcp_f32_e32 v141, v135
	v_mul_f32_e32 v135, 0xbfb8aa3b, v116
	v_add_f32_e32 v111, 1.0, v111
	v_exp_f32_e32 v135, v135
	v_rcp_f32_e32 v140, v111
	v_mul_f32_e32 v111, 0xbfb8aa3b, v115
	v_exp_f32_e32 v110, v110
	v_exp_f32_e32 v111, v111
	v_add_f32_e32 v135, 1.0, v135
	v_rcp_f32_e32 v142, v135
	v_mul_f32_e32 v135, 0xbfb8aa3b, v112
	v_add_f32_e32 v110, 1.0, v110
	v_add_f32_e32 v111, 1.0, v111
	v_exp_f32_e32 v135, v135
	v_rcp_f32_e32 v110, v110
	v_rcp_f32_e32 v111, v111
	v_mul_f32_e32 v136, v136, v140
	v_mul_f32_e32 v137, v137, v141
	v_add_f32_e32 v135, 1.0, v135
	v_rcp_f32_e32 v144, v135
	v_mul_f32_e32 v135, 0xbfb8aa3b, v117
	v_mul_f32_e32 v114, v114, v110
	v_mul_f32_e32 v115, v115, v111
	v_mul_f32_e32 v110, 0xbfb8aa3b, v113
	v_exp_f32_e32 v135, v135
	v_exp_f32_e32 v110, v110
	v_add_f32_e32 v135, 1.0, v135
	v_add_f32_e32 v110, 1.0, v110
	v_rcp_f32_e32 v143, v135
	v_rcp_f32_e32 v145, v110
	v_mul_f32_e32 v116, v116, v142
	v_mul_f32_e32 v117, v117, v143
	v_mul_f32_e32 v112, v112, v144
	v_mul_f32_e32 v113, v113, v145
.LBB0_351:
	v_add_u32_e32 v110, v165, v138
	v_ashrrev_i32_e32 v111, 31, v110
	v_mul_lo_u32 v138, s2, v111
	v_mul_lo_u32 v139, s3, v110
	v_mad_u64_u32 v[110:111], s[0:1], s2, v110, 0
	v_mov_b32_e32 v135, v134
	v_add3_u32 v111, v111, v138, v139
	v_cvt_pk_bf16_f32 v114, v114, v115
	v_cvt_pk_bf16_f32 v115, v116, v117
	v_cvt_pk_bf16_f32 v117, v112, v113
	v_mov_b32_e32 v112, v134
	v_mov_b32_e32 v113, v134
	v_lshl_add_u64 v[110:111], v[110:111], 1, v[168:169]
	v_cvt_pk_bf16_f32 v116, v136, v137
	v_mul_f32_e32 v108, v108, v112
	v_mul_f32_e32 v109, v109, v113
	v_mul_f32_e32 v106, v106, v134
	v_mul_f32_e32 v107, v107, v135
	v_mul_f32_e32 v104, v104, v112
	v_mul_f32_e32 v105, v105, v113
	s_and_b64 vcc, exec, s[46:47]
	v_mul_f32_e32 v102, v102, v134
	v_mul_f32_e32 v103, v103, v135
	global_store_dwordx4 v[110:111], v[114:117], off
	s_cbranch_vccnz .LBB0_353
	v_and_b32_e32 v113, 64, v218
	v_xor_b32_e32 v112, 16, v218
	v_add_u32_e32 v113, 64, v113
	v_cmp_lt_i32_e32 vcc, v112, v113
	s_nop 1
	v_cndmask_b32_e32 v112, v218, v112, vcc
	v_lshlrev_b32_e32 v135, 2, v112
	ds_bpermute_b32 v112, v135, v106
	ds_bpermute_b32 v113, v135, v107
	ds_bpermute_b32 v114, v135, v102
	ds_bpermute_b32 v116, v135, v108
	ds_bpermute_b32 v117, v135, v109
	ds_bpermute_b32 v115, v135, v103
	ds_bpermute_b32 v134, v135, v104
	ds_bpermute_b32 v135, v135, v105
	s_waitcnt lgkmcnt(6)
	v_mul_f32_e32 v112, v130, v112
	v_mul_f32_e32 v113, v131, v113
	s_waitcnt lgkmcnt(3)
	v_mul_f32_e32 v116, v132, v116
	v_mul_f32_e32 v117, v133, v117
	v_mul_f32_e32 v112, v156, v112
	v_mul_f32_e32 v113, v157, v113
	s_waitcnt lgkmcnt(2)
	v_mul_f32_e32 v114, v126, v114
	v_mul_f32_e32 v115, v127, v115
	v_fma_f32 v106, v106, v122, v112
	v_fma_f32 v107, v107, v123, v113
	s_waitcnt lgkmcnt(0)
	v_mul_f32_e32 v112, v128, v134
	v_mul_f32_e32 v113, v129, v135
	v_mul_f32_e32 v116, v158, v116
	v_mul_f32_e32 v117, v159, v117
	v_mul_f32_e32 v114, v156, v114
	v_mul_f32_e32 v115, v157, v115
	v_mul_f32_e32 v112, v158, v112
	v_mul_f32_e32 v113, v159, v113
	v_fma_f32 v108, v108, v124, v116
	v_fma_f32 v109, v109, v125, v117
	v_fma_f32 v104, v104, v120, v112
	v_fma_f32 v105, v105, v121, v113
	v_fma_f32 v102, v102, v118, v114
	v_fma_f32 v103, v103, v119, v115
.LBB0_353:
	s_and_b64 vcc, exec, s[48:49]
	s_cbranch_vccnz .LBB0_355
	v_mul_f32_e32 v113, 0xbfb8aa3b, v102
	v_exp_f32_e32 v113, v113
	v_mul_f32_e32 v112, 0xbfb8aa3b, v106
	v_exp_f32_e32 v112, v112
	v_mul_f32_e32 v117, 0xbfb8aa3b, v104
	v_add_f32_e32 v113, 1.0, v113
	v_rcp_f32_e32 v114, v113
	v_mul_f32_e32 v113, 0xbfb8aa3b, v107
	v_exp_f32_e32 v113, v113
	v_add_f32_e32 v112, 1.0, v112
	v_exp_f32_e32 v117, v117
	v_rcp_f32_e32 v112, v112
	v_add_f32_e32 v113, 1.0, v113
	v_rcp_f32_e32 v113, v113
	v_add_f32_e32 v117, 1.0, v117
	v_mul_f32_e32 v115, 0xbfb8aa3b, v103
	v_mul_f32_e32 v116, 0xbfb8aa3b, v108
	v_rcp_f32_e32 v118, v117
	v_mul_f32_e32 v117, 0xbfb8aa3b, v109
	v_mul_f32_e32 v106, v106, v112
	v_mul_f32_e32 v107, v107, v113
	v_mul_f32_e32 v112, 0xbfb8aa3b, v105
	v_exp_f32_e32 v115, v115
	v_exp_f32_e32 v116, v116
	v_exp_f32_e32 v117, v117
	v_exp_f32_e32 v112, v112
	v_add_f32_e32 v115, 1.0, v115
	v_add_f32_e32 v116, 1.0, v116
	v_add_f32_e32 v117, 1.0, v117
	v_add_f32_e32 v112, 1.0, v112
	v_rcp_f32_e32 v115, v115
	v_rcp_f32_e32 v116, v116
	v_rcp_f32_e32 v117, v117
	v_rcp_f32_e32 v119, v112
	v_mul_f32_e32 v102, v102, v114
	v_mul_f32_e32 v103, v103, v115
	v_mul_f32_e32 v108, v108, v116
	v_mul_f32_e32 v109, v109, v117
	v_mul_f32_e32 v104, v104, v118
	v_mul_f32_e32 v105, v105, v119

; __device__ __forceinline__ unsigned pk2(float lo, float hi) { f32x2v v = {lo, hi}; bf16x2_t b = __builtin_convertvector(v, bf16x2_t); return __builtin_bit_cast(unsigned, b); }
;     __device__ __forceinline__ void operator()(const pg8::f32x4 (&acc)[2][2][4][2], const pg8::Unit& u, int wr, int wc, int fr, int fq) const {
;     ...
;                 const int row = row0 + ai * 128 + m * 16;
;                 const int tok = row & (SEQ - 1);
;                 bf16_t* rowp = base + (size_t)((row >> 13) * LP + PADF + NMETA + tok) * ldc + col0;
;                 const float scr = sc * rstd[row];
;                 f32x4 c0 = {1.f, 1.f, 1.f, 1.f}, c1 = c0, s0 = {0.f, 0.f, 0.f, 0.f}, s1 = s0;
;                 if (dorope) {
;                     const int pos = NMETA + tok;
;                     if (fq < 2) { c0 = *(const f32x4*)(ropec + pos * 8); c1 = *(const f32x4*)(ropec + pos * 8 + 4); s0 = *(const f32x4*)(ropes + pos * 8); s1 = *(const f32x4*)(ropes + pos * 8 + 4); }
;                 }
; #pragma unroll
;                 for (int bj = 0; bj < 2; ++bj) {
;                     f32x4 v0 = acc[ai][bj][m][0] * scr, v1 = acc[ai][bj][m][1] * scr;
;                     if (dorope) {
;                         f32x4 p0, p1;
; #pragma unroll
;                         for (int e = 0; e < 4; ++e) { p0[e] = __shfl_xor(v0[e], 16); p1[e] = __shfl_xor(v1[e], 16); }
;                         v0 = v0 * c0 + (p0 * s0) * sgn; v1 = v1 * c1 + (p1 * s1) * sgn;
;                     }
;                     if (silu) {
; #pragma unroll
;                         for (int e = 0; e < 4; ++e) { v0[e] = v0[e] * __builtin_amdgcn_rcpf(1.f + __builtin_amdgcn_exp2f(-LOG2E * v0[e])); v1[e] = v1[e] * __builtin_amdgcn_rcpf(1.f + __builtin_amdgcn_exp2f(-LOG2E * v1[e])); }
;                     }
;                     u32x4 w; w.x = pk2(v0[0], v0[1]); w.y = pk2(v0[2], v0[3]); w.z = pk2(v1[0], v1[1]); w.w = pk2(v1[2], v1[3]);
;                     *(u32x4*)(rowp + bj * 128) = w;
.LBB0_357:
	s_or_b64 exec, exec, s[20:21]
	v_mul_f32_e32 v118, s19, v118
	v_mul_f32_e32 v100, v100, v118
	v_mul_f32_e32 v101, v101, v118
	v_mul_f32_e32 v98, v98, v118
	v_mul_f32_e32 v99, v99, v118
	v_mul_f32_e32 v96, v96, v118
	v_mul_f32_e32 v97, v97, v118
	s_and_b64 vcc, exec, s[46:47]
	v_mul_f32_e32 v120, v94, v118
	v_mul_f32_e32 v121, v95, v118
	s_cbranch_vccnz .LBB0_359
	v_and_b32_e32 v95, 64, v218
	v_xor_b32_e32 v94, 16, v218
	v_add_u32_e32 v95, 64, v95
	v_cmp_lt_i32_e32 vcc, v94, v95
	s_nop 1
	v_cndmask_b32_e32 v94, v218, v94, vcc
	v_lshlrev_b32_e32 v119, 2, v94
	ds_bpermute_b32 v94, v119, v98
	ds_bpermute_b32 v95, v119, v99
	ds_bpermute_b32 v124, v119, v120
	ds_bpermute_b32 v126, v119, v100
	ds_bpermute_b32 v127, v119, v101
	ds_bpermute_b32 v125, v119, v121
	ds_bpermute_b32 v128, v119, v96
	ds_bpermute_b32 v129, v119, v97
	s_waitcnt lgkmcnt(6)
	v_mul_f32_e32 v94, v114, v94
	v_mul_f32_e32 v95, v115, v95
	s_waitcnt lgkmcnt(3)
	v_mul_f32_e32 v126, v116, v126
	v_mul_f32_e32 v127, v117, v127
	v_mul_f32_e32 v94, v156, v94
	v_mul_f32_e32 v95, v157, v95
	s_waitcnt lgkmcnt(2)
	v_mul_f32_e32 v124, v110, v124
	v_mul_f32_e32 v125, v111, v125
	v_fma_f32 v98, v98, v106, v94
	v_fma_f32 v99, v99, v107, v95
	s_waitcnt lgkmcnt(0)
	v_mul_f32_e32 v94, v112, v128
	v_mul_f32_e32 v95, v113, v129
	v_mul_f32_e32 v126, v158, v126
	v_mul_f32_e32 v127, v159, v127
	v_mul_f32_e32 v124, v156, v124
	v_mul_f32_e32 v125, v157, v125
	v_mul_f32_e32 v94, v158, v94
	v_mul_f32_e32 v95, v159, v95
	v_fma_f32 v100, v100, v108, v126
	v_fma_f32 v101, v101, v109, v127
	v_fma_f32 v96, v96, v104, v94
	v_fma_f32 v97, v97, v105, v95
	v_fma_f32 v120, v120, v102, v124
	v_fma_f32 v121, v121, v103, v125
.LBB0_359:
	s_and_b64 vcc, exec, s[48:49]
	s_cbranch_vccnz .LBB0_361
	v_mul_f32_e32 v119, 0xbfb8aa3b, v121
	v_exp_f32_e32 v119, v119
	v_mul_f32_e32 v95, 0xbfb8aa3b, v120
	v_exp_f32_e32 v95, v95
	v_mul_f32_e32 v94, 0xbfb8aa3b, v98
	v_add_f32_e32 v119, 1.0, v119
	v_rcp_f32_e32 v125, v119
	v_mul_f32_e32 v119, 0xbfb8aa3b, v100
	v_add_f32_e32 v95, 1.0, v95
	v_exp_f32_e32 v119, v119
	v_rcp_f32_e32 v124, v95
	v_mul_f32_e32 v95, 0xbfb8aa3b, v99
	v_exp_f32_e32 v94, v94
	v_exp_f32_e32 v95, v95
	v_add_f32_e32 v119, 1.0, v119
	v_rcp_f32_e32 v126, v119
	v_mul_f32_e32 v119, 0xbfb8aa3b, v96
	v_add_f32_e32 v94, 1.0, v94
	v_add_f32_e32 v95, 1.0, v95
	v_exp_f32_e32 v119, v119
	v_rcp_f32_e32 v94, v94
	v_rcp_f32_e32 v95, v95
	v_mul_f32_e32 v120, v120, v124
	v_mul_f32_e32 v121, v121, v125
	v_add_f32_e32 v119, 1.0, v119
	v_rcp_f32_e32 v128, v119
	v_mul_f32_e32 v119, 0xbfb8aa3b, v101
	v_mul_f32_e32 v98, v98, v94
	v_mul_f32_e32 v99, v99, v95
	v_mul_f32_e32 v94, 0xbfb8aa3b, v97
	v_exp_f32_e32 v119, v119
	v_exp_f32_e32 v94, v94
	v_add_f32_e32 v119, 1.0, v119
	v_add_f32_e32 v94, 1.0, v94
	v_rcp_f32_e32 v127, v119
	v_rcp_f32_e32 v129, v94
	v_mul_f32_e32 v100, v100, v126
	v_mul_f32_e32 v101, v101, v127
	v_mul_f32_e32 v96, v96, v128
	v_mul_f32_e32 v97, v97, v129
.LBB0_361:
	v_add_u32_e32 v94, v165, v122
	v_ashrrev_i32_e32 v95, 31, v94
	v_mul_lo_u32 v122, s2, v95
	v_mul_lo_u32 v123, s3, v94
	v_mad_u64_u32 v[94:95], s[0:1], s2, v94, 0
	v_mov_b32_e32 v119, v118
	v_add3_u32 v95, v95, v122, v123
	v_cvt_pk_bf16_f32 v98, v98, v99
	v_cvt_pk_bf16_f32 v99, v100, v101
	v_cvt_pk_bf16_f32 v101, v96, v97
	v_mov_b32_e32 v96, v118
	v_mov_b32_e32 v97, v118
	v_lshl_add_u64 v[94:95], v[94:95], 1, v[168:169]
	v_cvt_pk_bf16_f32 v100, v120, v121
	v_mul_f32_e32 v92, v92, v96
	v_mul_f32_e32 v93, v93, v97
	v_mul_f32_e32 v90, v90, v118
	v_mul_f32_e32 v91, v91, v119
	v_mul_f32_e32 v88, v88, v96
	v_mul_f32_e32 v89, v89, v97
	s_and_b64 vcc, exec, s[46:47]
	v_mul_f32_e32 v86, v86, v118
	v_mul_f32_e32 v87, v87, v119
	global_store_dwordx4 v[94:95], v[98:101], off
	s_cbranch_vccnz .LBB0_363
	v_and_b32_e32 v97, 64, v218
	v_xor_b32_e32 v96, 16, v218
	v_add_u32_e32 v97, 64, v97
	v_cmp_lt_i32_e32 vcc, v96, v97
	s_nop 1
	v_cndmask_b32_e32 v96, v218, v96, vcc
	v_lshlrev_b32_e32 v119, 2, v96
	ds_bpermute_b32 v96, v119, v90
	ds_bpermute_b32 v97, v119, v91
	ds_bpermute_b32 v98, v119, v86
	ds_bpermute_b32 v100, v119, v92
	ds_bpermute_b32 v101, v119, v93
	ds_bpermute_b32 v99, v119, v87
	ds_bpermute_b32 v118, v119, v88
	ds_bpermute_b32 v119, v119, v89
	s_waitcnt lgkmcnt(6)
	v_mul_f32_e32 v96, v114, v96
	v_mul_f32_e32 v97, v115, v97
	s_waitcnt lgkmcnt(3)
	v_mul_f32_e32 v100, v116, v100
	v_mul_f32_e32 v101, v117, v101
	v_mul_f32_e32 v96, v156, v96
	v_mul_f32_e32 v97, v157, v97
	s_waitcnt lgkmcnt(2)
	v_mul_f32_e32 v98, v110, v98
	v_mul_f32_e32 v99, v111, v99
	v_fma_f32 v90, v90, v106, v96
	v_fma_f32 v91, v91, v107, v97
	s_waitcnt lgkmcnt(0)
	v_mul_f32_e32 v96, v112, v118
	v_mul_f32_e32 v97, v113, v119
	v_mul_f32_e32 v100, v158, v100
	v_mul_f32_e32 v101, v159, v101
	v_mul_f32_e32 v98, v156, v98
	v_mul_f32_e32 v99, v157, v99
	v_mul_f32_e32 v96, v158, v96
	v_mul_f32_e32 v97, v159, v97
	v_fma_f32 v92, v92, v108, v100
	v_fma_f32 v93, v93, v109, v101
	v_fma_f32 v88, v88, v104, v96
	v_fma_f32 v89, v89, v105, v97
	v_fma_f32 v86, v86, v102, v98
	v_fma_f32 v87, v87, v103, v99
.LBB0_363:
	s_and_b64 vcc, exec, s[48:49]
	s_cbranch_vccnz .LBB0_365
	v_mul_f32_e32 v97, 0xbfb8aa3b, v86
	v_exp_f32_e32 v97, v97
	v_mul_f32_e32 v96, 0xbfb8aa3b, v90
	v_exp_f32_e32 v96, v96
	v_mul_f32_e32 v101, 0xbfb8aa3b, v88
	v_add_f32_e32 v97, 1.0, v97
	v_rcp_f32_e32 v98, v97
	v_mul_f32_e32 v97, 0xbfb8aa3b, v91
	v_exp_f32_e32 v97, v97
	v_add_f32_e32 v96, 1.0, v96
	v_exp_f32_e32 v101, v101
	v_rcp_f32_e32 v96, v96
	v_add_f32_e32 v97, 1.0, v97
	v_rcp_f32_e32 v97, v97
	v_add_f32_e32 v101, 1.0, v101
	v_mul_f32_e32 v99, 0xbfb8aa3b, v87
	v_mul_f32_e32 v100, 0xbfb8aa3b, v92
	v_rcp_f32_e32 v102, v101
	v_mul_f32_e32 v101, 0xbfb8aa3b, v93
	v_mul_f32_e32 v90, v90, v96
	v_mul_f32_e32 v91, v91, v97
	v_mul_f32_e32 v96, 0xbfb8aa3b, v89
	v_exp_f32_e32 v99, v99
	v_exp_f32_e32 v100, v100
	v_exp_f32_e32 v101, v101
	v_exp_f32_e32 v96, v96
	v_add_f32_e32 v99, 1.0, v99
	v_add_f32_e32 v100, 1.0, v100
	v_add_f32_e32 v101, 1.0, v101
	v_add_f32_e32 v96, 1.0, v96
	v_rcp_f32_e32 v99, v99
	v_rcp_f32_e32 v100, v100
	v_rcp_f32_e32 v101, v101
	v_rcp_f32_e32 v103, v96
	v_mul_f32_e32 v86, v86, v98
	v_mul_f32_e32 v87, v87, v99
	v_mul_f32_e32 v92, v92, v100
	v_mul_f32_e32 v93, v93, v101
	v_mul_f32_e32 v88, v88, v102
	v_mul_f32_e32 v89, v89, v103

; __device__ __forceinline__ unsigned pk2(float lo, float hi) { f32x2v v = {lo, hi}; bf16x2_t b = __builtin_convertvector(v, bf16x2_t); return __builtin_bit_cast(unsigned, b); }
;     __device__ __forceinline__ void operator()(const pg8::f32x4 (&acc)[2][2][4][2], const pg8::Unit& u, int wr, int wc, int fr, int fq) const {
;     ...
;                 const int row = row0 + ai * 128 + m * 16;
;                 const int tok = row & (SEQ - 1);
;                 bf16_t* rowp = base + (size_t)((row >> 13) * LP + PADF + NMETA + tok) * ldc + col0;
;                 const float scr = sc * rstd[row];
;                 f32x4 c0 = {1.f, 1.f, 1.f, 1.f}, c1 = c0, s0 = {0.f, 0.f, 0.f, 0.f}, s1 = s0;
;                 if (dorope) {
;                     const int pos = NMETA + tok;
;                     if (fq < 2) { c0 = *(const f32x4*)(ropec + pos * 8); c1 = *(const f32x4*)(ropec + pos * 8 + 4); s0 = *(const f32x4*)(ropes + pos * 8); s1 = *(const f32x4*)(ropes + pos * 8 + 4); }
;                 }
; #pragma unroll
;                 for (int bj = 0; bj < 2; ++bj) {
;                     f32x4 v0 = acc[ai][bj][m][0] * scr, v1 = acc[ai][bj][m][1] * scr;
;                     if (dorope) {
;                         f32x4 p0, p1;
; #pragma unroll
;                         for (int e = 0; e < 4; ++e) { p0[e] = __shfl_xor(v0[e], 16); p1[e] = __shfl_xor(v1[e], 16); }
;                         v0 = v0 * c0 + (p0 * s0) * sgn; v1 = v1 * c1 + (p1 * s1) * sgn;
;                     }
;                     if (silu) {
; #pragma unroll
;                         for (int e = 0; e < 4; ++e) { v0[e] = v0[e] * __builtin_amdgcn_rcpf(1.f + __builtin_amdgcn_exp2f(-LOG2E * v0[e])); v1[e] = v1[e] * __builtin_amdgcn_rcpf(1.f + __builtin_amdgcn_exp2f(-LOG2E * v1[e])); }
;                     }
;                     u32x4 w; w.x = pk2(v0[0], v0[1]); w.y = pk2(v0[2], v0[3]); w.z = pk2(v1[0], v1[1]); w.w = pk2(v1[2], v1[3]);
;                     *(u32x4*)(rowp + bj * 128) = w;
.LBB0_367:
	s_or_b64 exec, exec, s[20:21]
	v_mul_f32_e32 v102, s19, v102
	v_mul_f32_e32 v84, v84, v102
	v_mul_f32_e32 v85, v85, v102
	v_mul_f32_e32 v82, v82, v102
	v_mul_f32_e32 v83, v83, v102
	v_mul_f32_e32 v80, v80, v102
	v_mul_f32_e32 v81, v81, v102
	s_and_b64 vcc, exec, s[46:47]
	v_mul_f32_e32 v104, v78, v102
	v_mul_f32_e32 v105, v79, v102
	s_cbranch_vccnz .LBB0_369
	v_and_b32_e32 v79, 64, v218
	v_xor_b32_e32 v78, 16, v218
	v_add_u32_e32 v79, 64, v79
	v_cmp_lt_i32_e32 vcc, v78, v79
	s_nop 1
	v_cndmask_b32_e32 v78, v218, v78, vcc
	v_lshlrev_b32_e32 v103, 2, v78
	ds_bpermute_b32 v78, v103, v82
	ds_bpermute_b32 v79, v103, v83
	ds_bpermute_b32 v108, v103, v104
	ds_bpermute_b32 v110, v103, v84
	ds_bpermute_b32 v111, v103, v85
	ds_bpermute_b32 v109, v103, v105
	ds_bpermute_b32 v112, v103, v80
	ds_bpermute_b32 v113, v103, v81
	s_waitcnt lgkmcnt(6)
	v_mul_f32_e32 v78, v98, v78
	v_mul_f32_e32 v79, v99, v79
	s_waitcnt lgkmcnt(3)
	v_mul_f32_e32 v110, v100, v110
	v_mul_f32_e32 v111, v101, v111
	v_mul_f32_e32 v78, v156, v78
	v_mul_f32_e32 v79, v157, v79
	s_waitcnt lgkmcnt(2)
	v_mul_f32_e32 v108, v94, v108
	v_mul_f32_e32 v109, v95, v109
	v_fma_f32 v82, v82, v90, v78
	v_fma_f32 v83, v83, v91, v79
	s_waitcnt lgkmcnt(0)
	v_mul_f32_e32 v78, v96, v112
	v_mul_f32_e32 v79, v97, v113
	v_mul_f32_e32 v110, v158, v110
	v_mul_f32_e32 v111, v159, v111
	v_mul_f32_e32 v108, v156, v108
	v_mul_f32_e32 v109, v157, v109
	v_mul_f32_e32 v78, v158, v78
	v_mul_f32_e32 v79, v159, v79
	v_fma_f32 v84, v84, v92, v110
	v_fma_f32 v85, v85, v93, v111
	v_fma_f32 v80, v80, v88, v78
	v_fma_f32 v81, v81, v89, v79
	v_fma_f32 v104, v104, v86, v108
	v_fma_f32 v105, v105, v87, v109
.LBB0_369:
	s_and_b64 vcc, exec, s[48:49]
	s_cbranch_vccnz .LBB0_371
	v_mul_f32_e32 v103, 0xbfb8aa3b, v105
	v_exp_f32_e32 v103, v103
	v_mul_f32_e32 v79, 0xbfb8aa3b, v104
	v_exp_f32_e32 v79, v79
	v_mul_f32_e32 v78, 0xbfb8aa3b, v82
	v_add_f32_e32 v103, 1.0, v103
	v_rcp_f32_e32 v109, v103
	v_mul_f32_e32 v103, 0xbfb8aa3b, v84
	v_add_f32_e32 v79, 1.0, v79
	v_exp_f32_e32 v103, v103
	v_rcp_f32_e32 v108, v79
	v_mul_f32_e32 v79, 0xbfb8aa3b, v83
	v_exp_f32_e32 v78, v78
	v_exp_f32_e32 v79, v79
	v_add_f32_e32 v103, 1.0, v103
	v_rcp_f32_e32 v110, v103
	v_mul_f32_e32 v103, 0xbfb8aa3b, v80
	v_add_f32_e32 v78, 1.0, v78
	v_add_f32_e32 v79, 1.0, v79
	v_exp_f32_e32 v103, v103
	v_rcp_f32_e32 v78, v78
	v_rcp_f32_e32 v79, v79
	v_mul_f32_e32 v104, v104, v108
	v_mul_f32_e32 v105, v105, v109
	v_add_f32_e32 v103, 1.0, v103
	v_rcp_f32_e32 v112, v103
	v_mul_f32_e32 v103, 0xbfb8aa3b, v85
	v_mul_f32_e32 v82, v82, v78
	v_mul_f32_e32 v83, v83, v79
	v_mul_f32_e32 v78, 0xbfb8aa3b, v81
	v_exp_f32_e32 v103, v103
	v_exp_f32_e32 v78, v78
	v_add_f32_e32 v103, 1.0, v103
	v_add_f32_e32 v78, 1.0, v78
	v_rcp_f32_e32 v111, v103
	v_rcp_f32_e32 v113, v78
	v_mul_f32_e32 v84, v84, v110
	v_mul_f32_e32 v85, v85, v111
	v_mul_f32_e32 v80, v80, v112
	v_mul_f32_e32 v81, v81, v113
.LBB0_371:
	v_add_u32_e32 v78, v165, v106
	v_ashrrev_i32_e32 v79, 31, v78
	v_mul_lo_u32 v106, s2, v79
	v_mul_lo_u32 v107, s3, v78
	v_mad_u64_u32 v[78:79], s[0:1], s2, v78, 0
	v_mov_b32_e32 v103, v102
	v_add3_u32 v79, v79, v106, v107
	v_cvt_pk_bf16_f32 v82, v82, v83
	v_cvt_pk_bf16_f32 v83, v84, v85
	v_cvt_pk_bf16_f32 v85, v80, v81
	v_mov_b32_e32 v80, v102
	v_mov_b32_e32 v81, v102
	v_lshl_add_u64 v[78:79], v[78:79], 1, v[168:169]
	v_cvt_pk_bf16_f32 v84, v104, v105
	v_mul_f32_e32 v76, v76, v80
	v_mul_f32_e32 v77, v77, v81
	v_mul_f32_e32 v74, v74, v102
	v_mul_f32_e32 v75, v75, v103
	v_mul_f32_e32 v72, v72, v80
	v_mul_f32_e32 v73, v73, v81
	s_and_b64 vcc, exec, s[46:47]
	v_mul_f32_e32 v70, v70, v102
	v_mul_f32_e32 v71, v71, v103
	global_store_dwordx4 v[78:79], v[82:85], off
	s_cbranch_vccnz .LBB0_373
	v_and_b32_e32 v81, 64, v218
	v_xor_b32_e32 v80, 16, v218
	v_add_u32_e32 v81, 64, v81
	v_cmp_lt_i32_e32 vcc, v80, v81
	s_nop 1
	v_cndmask_b32_e32 v80, v218, v80, vcc
	v_lshlrev_b32_e32 v103, 2, v80
	ds_bpermute_b32 v80, v103, v74
	ds_bpermute_b32 v81, v103, v75
	ds_bpermute_b32 v82, v103, v70
	ds_bpermute_b32 v84, v103, v76
	ds_bpermute_b32 v85, v103, v77
	ds_bpermute_b32 v83, v103, v71
	ds_bpermute_b32 v102, v103, v72
	ds_bpermute_b32 v103, v103, v73
	s_waitcnt lgkmcnt(6)
	v_mul_f32_e32 v80, v98, v80
	v_mul_f32_e32 v81, v99, v81
	s_waitcnt lgkmcnt(3)
	v_mul_f32_e32 v84, v100, v84
	v_mul_f32_e32 v85, v101, v85
	v_mul_f32_e32 v80, v156, v80
	v_mul_f32_e32 v81, v157, v81
	s_waitcnt lgkmcnt(2)
	v_mul_f32_e32 v82, v94, v82
	v_mul_f32_e32 v83, v95, v83
	v_fma_f32 v74, v74, v90, v80
	v_fma_f32 v75, v75, v91, v81
	s_waitcnt lgkmcnt(0)
	v_mul_f32_e32 v80, v96, v102
	v_mul_f32_e32 v81, v97, v103
	v_mul_f32_e32 v84, v158, v84
	v_mul_f32_e32 v85, v159, v85
	v_mul_f32_e32 v82, v156, v82
	v_mul_f32_e32 v83, v157, v83
	v_mul_f32_e32 v80, v158, v80
	v_mul_f32_e32 v81, v159, v81
	v_fma_f32 v76, v76, v92, v84
	v_fma_f32 v77, v77, v93, v85
	v_fma_f32 v72, v72, v88, v80
	v_fma_f32 v73, v73, v89, v81
	v_fma_f32 v70, v70, v86, v82
	v_fma_f32 v71, v71, v87, v83
.LBB0_373:
	s_and_b64 vcc, exec, s[48:49]
	s_cbranch_vccnz .LBB0_375
	v_mul_f32_e32 v81, 0xbfb8aa3b, v70
	v_exp_f32_e32 v81, v81
	v_mul_f32_e32 v80, 0xbfb8aa3b, v74
	v_exp_f32_e32 v80, v80
	v_mul_f32_e32 v85, 0xbfb8aa3b, v72
	v_add_f32_e32 v81, 1.0, v81
	v_rcp_f32_e32 v82, v81
	v_mul_f32_e32 v81, 0xbfb8aa3b, v75
	v_exp_f32_e32 v81, v81
	v_add_f32_e32 v80, 1.0, v80
	v_exp_f32_e32 v85, v85
	v_rcp_f32_e32 v80, v80
	v_add_f32_e32 v81, 1.0, v81
	v_rcp_f32_e32 v81, v81
	v_add_f32_e32 v85, 1.0, v85
	v_mul_f32_e32 v83, 0xbfb8aa3b, v71
	v_mul_f32_e32 v84, 0xbfb8aa3b, v76
	v_rcp_f32_e32 v86, v85
	v_mul_f32_e32 v85, 0xbfb8aa3b, v77
	v_mul_f32_e32 v74, v74, v80
	v_mul_f32_e32 v75, v75, v81
	v_mul_f32_e32 v80, 0xbfb8aa3b, v73
	v_exp_f32_e32 v83, v83
	v_exp_f32_e32 v84, v84
	v_exp_f32_e32 v85, v85
	v_exp_f32_e32 v80, v80
	v_add_f32_e32 v83, 1.0, v83
	v_add_f32_e32 v84, 1.0, v84
	v_add_f32_e32 v85, 1.0, v85
	v_add_f32_e32 v80, 1.0, v80
	v_rcp_f32_e32 v83, v83
	v_rcp_f32_e32 v84, v84
	v_rcp_f32_e32 v85, v85
	v_rcp_f32_e32 v87, v80
	v_mul_f32_e32 v70, v70, v82
	v_mul_f32_e32 v71, v71, v83
	v_mul_f32_e32 v76, v76, v84
	v_mul_f32_e32 v77, v77, v85
	v_mul_f32_e32 v72, v72, v86
	v_mul_f32_e32 v73, v73, v87

; __device__ __forceinline__ unsigned pk2(float lo, float hi) { f32x2v v = {lo, hi}; bf16x2_t b = __builtin_convertvector(v, bf16x2_t); return __builtin_bit_cast(unsigned, b); }
;     __device__ __forceinline__ void operator()(const pg8::f32x4 (&acc)[2][2][4][2], const pg8::Unit& u, int wr, int wc, int fr, int fq) const {
;     ...
;                 const int row = row0 + ai * 128 + m * 16;
;                 const int tok = row & (SEQ - 1);
;                 bf16_t* rowp = base + (size_t)((row >> 13) * LP + PADF + NMETA + tok) * ldc + col0;
;                 const float scr = sc * rstd[row];
;                 f32x4 c0 = {1.f, 1.f, 1.f, 1.f}, c1 = c0, s0 = {0.f, 0.f, 0.f, 0.f}, s1 = s0;
;                 if (dorope) {
;                     const int pos = NMETA + tok;
;                     if (fq < 2) { c0 = *(const f32x4*)(ropec + pos * 8); c1 = *(const f32x4*)(ropec + pos * 8 + 4); s0 = *(const f32x4*)(ropes + pos * 8); s1 = *(const f32x4*)(ropes + pos * 8 + 4); }
;                 }
; #pragma unroll
;                 for (int bj = 0; bj < 2; ++bj) {
;                     f32x4 v0 = acc[ai][bj][m][0] * scr, v1 = acc[ai][bj][m][1] * scr;
;                     if (dorope) {
;                         f32x4 p0, p1;
; #pragma unroll
;                         for (int e = 0; e < 4; ++e) { p0[e] = __shfl_xor(v0[e], 16); p1[e] = __shfl_xor(v1[e], 16); }
;                         v0 = v0 * c0 + (p0 * s0) * sgn; v1 = v1 * c1 + (p1 * s1) * sgn;
;                     }
;                     if (silu) {
; #pragma unroll
;                         for (int e = 0; e < 4; ++e) { v0[e] = v0[e] * __builtin_amdgcn_rcpf(1.f + __builtin_amdgcn_exp2f(-LOG2E * v0[e])); v1[e] = v1[e] * __builtin_amdgcn_rcpf(1.f + __builtin_amdgcn_exp2f(-LOG2E * v1[e])); }
;                     }
;                     u32x4 w; w.x = pk2(v0[0], v0[1]); w.y = pk2(v0[2], v0[3]); w.z = pk2(v1[0], v1[1]); w.w = pk2(v1[2], v1[3]);
;                     *(u32x4*)(rowp + bj * 128) = w;
.LBB0_377:
	s_or_b64 exec, exec, s[20:21]
	v_mul_f32_e32 v88, s19, v88
	v_mul_f32_e32 v68, v68, v88
	v_mul_f32_e32 v69, v69, v88
	v_mul_f32_e32 v66, v66, v88
	v_mul_f32_e32 v67, v67, v88
	v_mul_f32_e32 v64, v64, v88
	v_mul_f32_e32 v65, v65, v88
	s_and_b64 vcc, exec, s[46:47]
	v_mul_f32_e32 v90, v62, v88
	v_mul_f32_e32 v91, v63, v88
	s_cbranch_vccnz .LBB0_379
	v_and_b32_e32 v63, 64, v218
	v_xor_b32_e32 v62, 16, v218
	v_add_u32_e32 v63, 64, v63
	v_cmp_lt_i32_e32 vcc, v62, v63
	s_nop 1
	v_cndmask_b32_e32 v62, v218, v62, vcc
	v_lshlrev_b32_e32 v89, 2, v62
	ds_bpermute_b32 v62, v89, v66
	ds_bpermute_b32 v63, v89, v67
	ds_bpermute_b32 v92, v89, v90
	ds_bpermute_b32 v94, v89, v68
	ds_bpermute_b32 v95, v89, v69
	ds_bpermute_b32 v93, v89, v91
	ds_bpermute_b32 v96, v89, v64
	ds_bpermute_b32 v97, v89, v65
	s_waitcnt lgkmcnt(6)
	v_mul_f32_e32 v62, v82, v62
	v_mul_f32_e32 v63, v83, v63
	s_waitcnt lgkmcnt(3)
	v_mul_f32_e32 v94, v84, v94
	v_mul_f32_e32 v95, v85, v95
	v_mul_f32_e32 v62, v156, v62
	v_mul_f32_e32 v63, v157, v63
	s_waitcnt lgkmcnt(2)
	v_mul_f32_e32 v92, v78, v92
	v_mul_f32_e32 v93, v79, v93
	v_fma_f32 v66, v66, v74, v62
	v_fma_f32 v67, v67, v75, v63
	s_waitcnt lgkmcnt(0)
	v_mul_f32_e32 v62, v80, v96
	v_mul_f32_e32 v63, v81, v97
	v_mul_f32_e32 v94, v158, v94
	v_mul_f32_e32 v95, v159, v95
	v_mul_f32_e32 v92, v156, v92
	v_mul_f32_e32 v93, v157, v93
	v_mul_f32_e32 v62, v158, v62
	v_mul_f32_e32 v63, v159, v63
	v_fma_f32 v68, v68, v76, v94
	v_fma_f32 v69, v69, v77, v95
	v_fma_f32 v64, v64, v72, v62
	v_fma_f32 v65, v65, v73, v63
	v_fma_f32 v90, v90, v70, v92
	v_fma_f32 v91, v91, v71, v93
.LBB0_379:
	s_and_b64 vcc, exec, s[48:49]
	s_cbranch_vccnz .LBB0_381
	v_mul_f32_e32 v89, 0xbfb8aa3b, v91
	v_exp_f32_e32 v89, v89
	v_mul_f32_e32 v63, 0xbfb8aa3b, v90
	v_exp_f32_e32 v63, v63
	v_mul_f32_e32 v62, 0xbfb8aa3b, v66
	v_add_f32_e32 v89, 1.0, v89
	v_rcp_f32_e32 v93, v89
	v_mul_f32_e32 v89, 0xbfb8aa3b, v68
	v_add_f32_e32 v63, 1.0, v63
	v_exp_f32_e32 v89, v89
	v_rcp_f32_e32 v92, v63
	v_mul_f32_e32 v63, 0xbfb8aa3b, v67
	v_exp_f32_e32 v62, v62
	v_exp_f32_e32 v63, v63
	v_add_f32_e32 v89, 1.0, v89
	v_rcp_f32_e32 v94, v89
	v_mul_f32_e32 v89, 0xbfb8aa3b, v64
	v_add_f32_e32 v62, 1.0, v62
	v_add_f32_e32 v63, 1.0, v63
	v_exp_f32_e32 v89, v89
	v_rcp_f32_e32 v62, v62
	v_rcp_f32_e32 v63, v63
	v_mul_f32_e32 v90, v90, v92
	v_mul_f32_e32 v91, v91, v93
	v_add_f32_e32 v89, 1.0, v89
	v_rcp_f32_e32 v96, v89
	v_mul_f32_e32 v89, 0xbfb8aa3b, v69
	v_mul_f32_e32 v66, v66, v62
	v_mul_f32_e32 v67, v67, v63
	v_mul_f32_e32 v62, 0xbfb8aa3b, v65
	v_exp_f32_e32 v89, v89
	v_exp_f32_e32 v62, v62
	v_add_f32_e32 v89, 1.0, v89
	v_add_f32_e32 v62, 1.0, v62
	v_rcp_f32_e32 v95, v89
	v_rcp_f32_e32 v97, v62
	v_mul_f32_e32 v68, v68, v94
	v_mul_f32_e32 v69, v69, v95
	v_mul_f32_e32 v64, v64, v96
	v_mul_f32_e32 v65, v65, v97
.LBB0_381:
	v_ashrrev_i32_e32 v62, 13, v86
	s_movk_i32 s0, 0x2080
	v_mad_i32_i24 v86, v62, s0, v221
	v_add_u32_e32 v62, v86, v87
	v_ashrrev_i32_e32 v63, 31, v62
	v_mul_lo_u32 v87, s2, v63
	v_mul_lo_u32 v92, s3, v62
	v_mad_u64_u32 v[62:63], s[0:1], s2, v62, 0
	v_mov_b32_e32 v89, v88
	v_add3_u32 v63, v63, v87, v92
	v_cvt_pk_bf16_f32 v66, v66, v67
	v_cvt_pk_bf16_f32 v67, v68, v69
	v_cvt_pk_bf16_f32 v69, v64, v65
	v_mov_b32_e32 v64, v88
	v_mov_b32_e32 v65, v88
	v_lshl_add_u64 v[62:63], v[62:63], 1, v[168:169]
	v_cvt_pk_bf16_f32 v68, v90, v91
	v_mul_f32_e32 v60, v60, v64
	v_mul_f32_e32 v61, v61, v65
	v_mul_f32_e32 v58, v58, v88
	v_mul_f32_e32 v59, v59, v89
	v_mul_f32_e32 v56, v56, v64
	v_mul_f32_e32 v57, v57, v65
	s_and_b64 vcc, exec, s[46:47]
	v_mul_f32_e32 v54, v54, v88
	v_mul_f32_e32 v55, v55, v89
	global_store_dwordx4 v[62:63], v[66:69], off
	s_cbranch_vccnz .LBB0_383
	v_and_b32_e32 v65, 64, v218
	v_xor_b32_e32 v64, 16, v218
	v_add_u32_e32 v65, 64, v65
	v_cmp_lt_i32_e32 vcc, v64, v65
	s_nop 1
	v_cndmask_b32_e32 v64, v218, v64, vcc
	v_lshlrev_b32_e32 v87, 2, v64
	ds_bpermute_b32 v64, v87, v58
	ds_bpermute_b32 v65, v87, v59
	ds_bpermute_b32 v66, v87, v54
	ds_bpermute_b32 v68, v87, v60
	ds_bpermute_b32 v69, v87, v61
	ds_bpermute_b32 v67, v87, v55
	ds_bpermute_b32 v88, v87, v56
	ds_bpermute_b32 v89, v87, v57
	s_waitcnt lgkmcnt(6)
	v_mul_f32_e32 v64, v82, v64
	v_mul_f32_e32 v65, v83, v65
	s_waitcnt lgkmcnt(3)
	v_mul_f32_e32 v68, v84, v68
	v_mul_f32_e32 v69, v85, v69
	v_mul_f32_e32 v64, v156, v64
	v_mul_f32_e32 v65, v157, v65
	s_waitcnt lgkmcnt(2)
	v_mul_f32_e32 v66, v78, v66
	v_mul_f32_e32 v67, v79, v67
	v_fma_f32 v58, v58, v74, v64
	v_fma_f32 v59, v59, v75, v65
	s_waitcnt lgkmcnt(0)
	v_mul_f32_e32 v64, v80, v88
	v_mul_f32_e32 v65, v81, v89
	v_mul_f32_e32 v68, v158, v68
	v_mul_f32_e32 v69, v159, v69
	v_mul_f32_e32 v66, v156, v66
	v_mul_f32_e32 v67, v157, v67
	v_mul_f32_e32 v64, v158, v64
	v_mul_f32_e32 v65, v159, v65
	v_fma_f32 v60, v60, v76, v68
	v_fma_f32 v61, v61, v77, v69
	v_fma_f32 v56, v56, v72, v64
	v_fma_f32 v57, v57, v73, v65
	v_fma_f32 v54, v54, v70, v66
	v_fma_f32 v55, v55, v71, v67
.LBB0_383:
	s_and_b64 vcc, exec, s[48:49]
	s_cbranch_vccnz .LBB0_385
	v_mul_f32_e32 v65, 0xbfb8aa3b, v54
	v_exp_f32_e32 v65, v65
	v_mul_f32_e32 v64, 0xbfb8aa3b, v58
	v_exp_f32_e32 v64, v64
	v_mul_f32_e32 v69, 0xbfb8aa3b, v56
	v_add_f32_e32 v65, 1.0, v65
	v_rcp_f32_e32 v66, v65
	v_mul_f32_e32 v65, 0xbfb8aa3b, v59
	v_exp_f32_e32 v65, v65
	v_add_f32_e32 v64, 1.0, v64
	v_exp_f32_e32 v69, v69
	v_rcp_f32_e32 v64, v64
	v_add_f32_e32 v65, 1.0, v65
	v_rcp_f32_e32 v65, v65
	v_add_f32_e32 v69, 1.0, v69
	v_mul_f32_e32 v67, 0xbfb8aa3b, v55
	v_mul_f32_e32 v68, 0xbfb8aa3b, v60
	v_rcp_f32_e32 v70, v69
	v_mul_f32_e32 v69, 0xbfb8aa3b, v61
	v_mul_f32_e32 v58, v58, v64
	v_mul_f32_e32 v59, v59, v65
	v_mul_f32_e32 v64, 0xbfb8aa3b, v57
	v_exp_f32_e32 v67, v67
	v_exp_f32_e32 v68, v68
	v_exp_f32_e32 v69, v69
	v_exp_f32_e32 v64, v64
	v_add_f32_e32 v67, 1.0, v67
	v_add_f32_e32 v68, 1.0, v68
	v_add_f32_e32 v69, 1.0, v69
	v_add_f32_e32 v64, 1.0, v64
	v_rcp_f32_e32 v67, v67
	v_rcp_f32_e32 v68, v68
	v_rcp_f32_e32 v69, v69
	v_rcp_f32_e32 v71, v64
	v_mul_f32_e32 v54, v54, v66
	v_mul_f32_e32 v55, v55, v67
	v_mul_f32_e32 v60, v60, v68
	v_mul_f32_e32 v61, v61, v69
	v_mul_f32_e32 v56, v56, v70
	v_mul_f32_e32 v57, v57, v71

; __device__ __forceinline__ unsigned pk2(float lo, float hi) { f32x2v v = {lo, hi}; bf16x2_t b = __builtin_convertvector(v, bf16x2_t); return __builtin_bit_cast(unsigned, b); }
;     __device__ __forceinline__ void operator()(const pg8::f32x4 (&acc)[2][2][4][2], const pg8::Unit& u, int wr, int wc, int fr, int fq) const {
;     ...
;                 const int row = row0 + ai * 128 + m * 16;
;                 const int tok = row & (SEQ - 1);
;                 bf16_t* rowp = base + (size_t)((row >> 13) * LP + PADF + NMETA + tok) * ldc + col0;
;                 const float scr = sc * rstd[row];
;                 f32x4 c0 = {1.f, 1.f, 1.f, 1.f}, c1 = c0, s0 = {0.f, 0.f, 0.f, 0.f}, s1 = s0;
;                 if (dorope) {
;                     const int pos = NMETA + tok;
;                     if (fq < 2) { c0 = *(const f32x4*)(ropec + pos * 8); c1 = *(const f32x4*)(ropec + pos * 8 + 4); s0 = *(const f32x4*)(ropes + pos * 8); s1 = *(const f32x4*)(ropes + pos * 8 + 4); }
;                 }
; #pragma unroll
;                 for (int bj = 0; bj < 2; ++bj) {
;                     f32x4 v0 = acc[ai][bj][m][0] * scr, v1 = acc[ai][bj][m][1] * scr;
;                     if (dorope) {
;                         f32x4 p0, p1;
; #pragma unroll
;                         for (int e = 0; e < 4; ++e) { p0[e] = __shfl_xor(v0[e], 16); p1[e] = __shfl_xor(v1[e], 16); }
;                         v0 = v0 * c0 + (p0 * s0) * sgn; v1 = v1 * c1 + (p1 * s1) * sgn;
;                     }
;                     if (silu) {
; #pragma unroll
;                         for (int e = 0; e < 4; ++e) { v0[e] = v0[e] * __builtin_amdgcn_rcpf(1.f + __builtin_amdgcn_exp2f(-LOG2E * v0[e])); v1[e] = v1[e] * __builtin_amdgcn_rcpf(1.f + __builtin_amdgcn_exp2f(-LOG2E * v1[e])); }
;                     }
;                     u32x4 w; w.x = pk2(v0[0], v0[1]); w.y = pk2(v0[2], v0[3]); w.z = pk2(v1[0], v1[1]); w.w = pk2(v1[2], v1[3]);
;                     *(u32x4*)(rowp + bj * 128) = w;
.LBB0_387:
	s_or_b64 exec, exec, s[20:21]
	v_mul_f32_e32 v70, s19, v70
	v_mul_f32_e32 v52, v52, v70
	v_mul_f32_e32 v53, v53, v70
	v_mul_f32_e32 v50, v50, v70
	v_mul_f32_e32 v51, v51, v70
	v_mul_f32_e32 v48, v48, v70
	v_mul_f32_e32 v49, v49, v70
	s_and_b64 vcc, exec, s[46:47]
	v_mul_f32_e32 v72, v46, v70
	v_mul_f32_e32 v73, v47, v70
	s_cbranch_vccnz .LBB0_389
	v_and_b32_e32 v47, 64, v218
	v_xor_b32_e32 v46, 16, v218
	v_add_u32_e32 v47, 64, v47
	v_cmp_lt_i32_e32 vcc, v46, v47
	s_nop 1
	v_cndmask_b32_e32 v46, v218, v46, vcc
	v_lshlrev_b32_e32 v71, 2, v46
	ds_bpermute_b32 v46, v71, v50
	ds_bpermute_b32 v47, v71, v51
	ds_bpermute_b32 v76, v71, v72
	ds_bpermute_b32 v78, v71, v52
	ds_bpermute_b32 v79, v71, v53
	ds_bpermute_b32 v77, v71, v73
	ds_bpermute_b32 v80, v71, v48
	ds_bpermute_b32 v81, v71, v49
	s_waitcnt lgkmcnt(6)
	v_mul_f32_e32 v46, v66, v46
	v_mul_f32_e32 v47, v67, v47
	s_waitcnt lgkmcnt(3)
	v_mul_f32_e32 v78, v68, v78
	v_mul_f32_e32 v79, v69, v79
	v_mul_f32_e32 v46, v156, v46
	v_mul_f32_e32 v47, v157, v47
	s_waitcnt lgkmcnt(2)
	v_mul_f32_e32 v76, v62, v76
	v_mul_f32_e32 v77, v63, v77
	v_fma_f32 v50, v50, v58, v46
	v_fma_f32 v51, v51, v59, v47
	s_waitcnt lgkmcnt(0)
	v_mul_f32_e32 v46, v64, v80
	v_mul_f32_e32 v47, v65, v81
	v_mul_f32_e32 v78, v158, v78
	v_mul_f32_e32 v79, v159, v79
	v_mul_f32_e32 v76, v156, v76
	v_mul_f32_e32 v77, v157, v77
	v_mul_f32_e32 v46, v158, v46
	v_mul_f32_e32 v47, v159, v47
	v_fma_f32 v52, v52, v60, v78
	v_fma_f32 v53, v53, v61, v79
	v_fma_f32 v48, v48, v56, v46
	v_fma_f32 v49, v49, v57, v47
	v_fma_f32 v72, v72, v54, v76
	v_fma_f32 v73, v73, v55, v77
.LBB0_389:
	s_and_b64 vcc, exec, s[48:49]
	s_cbranch_vccnz .LBB0_391
	v_mul_f32_e32 v71, 0xbfb8aa3b, v73
	v_exp_f32_e32 v71, v71
	v_mul_f32_e32 v47, 0xbfb8aa3b, v72
	v_exp_f32_e32 v47, v47
	v_mul_f32_e32 v46, 0xbfb8aa3b, v50
	v_add_f32_e32 v71, 1.0, v71
	v_rcp_f32_e32 v77, v71
	v_mul_f32_e32 v71, 0xbfb8aa3b, v52
	v_add_f32_e32 v47, 1.0, v47
	v_exp_f32_e32 v71, v71
	v_rcp_f32_e32 v76, v47
	v_mul_f32_e32 v47, 0xbfb8aa3b, v51
	v_exp_f32_e32 v46, v46
	v_exp_f32_e32 v47, v47
	v_add_f32_e32 v71, 1.0, v71
	v_rcp_f32_e32 v78, v71
	v_mul_f32_e32 v71, 0xbfb8aa3b, v48
	v_add_f32_e32 v46, 1.0, v46
	v_add_f32_e32 v47, 1.0, v47
	v_exp_f32_e32 v71, v71
	v_rcp_f32_e32 v46, v46
	v_rcp_f32_e32 v47, v47
	v_mul_f32_e32 v72, v72, v76
	v_mul_f32_e32 v73, v73, v77
	v_add_f32_e32 v71, 1.0, v71
	v_rcp_f32_e32 v80, v71
	v_mul_f32_e32 v71, 0xbfb8aa3b, v53
	v_mul_f32_e32 v50, v50, v46
	v_mul_f32_e32 v51, v51, v47
	v_mul_f32_e32 v46, 0xbfb8aa3b, v49
	v_exp_f32_e32 v71, v71
	v_exp_f32_e32 v46, v46
	v_add_f32_e32 v71, 1.0, v71
	v_add_f32_e32 v46, 1.0, v46
	v_rcp_f32_e32 v79, v71
	v_rcp_f32_e32 v81, v46
	v_mul_f32_e32 v52, v52, v78
	v_mul_f32_e32 v53, v53, v79
	v_mul_f32_e32 v48, v48, v80
	v_mul_f32_e32 v49, v49, v81
.LBB0_391:
	v_add_u32_e32 v46, v86, v74
	v_ashrrev_i32_e32 v47, 31, v46
	v_mul_lo_u32 v74, s2, v47
	v_mul_lo_u32 v75, s3, v46
	v_mad_u64_u32 v[46:47], s[0:1], s2, v46, 0
	v_mov_b32_e32 v71, v70
	v_add3_u32 v47, v47, v74, v75
	v_cvt_pk_bf16_f32 v50, v50, v51
	v_cvt_pk_bf16_f32 v51, v52, v53
	v_cvt_pk_bf16_f32 v53, v48, v49
	v_mov_b32_e32 v48, v70
	v_mov_b32_e32 v49, v70
	v_lshl_add_u64 v[46:47], v[46:47], 1, v[168:169]
	v_cvt_pk_bf16_f32 v52, v72, v73
	v_mul_f32_e32 v44, v44, v48
	v_mul_f32_e32 v45, v45, v49
	v_mul_f32_e32 v42, v42, v70
	v_mul_f32_e32 v43, v43, v71
	v_mul_f32_e32 v40, v40, v48
	v_mul_f32_e32 v41, v41, v49
	s_and_b64 vcc, exec, s[46:47]
	v_mul_f32_e32 v38, v38, v70
	v_mul_f32_e32 v39, v39, v71
	global_store_dwordx4 v[46:47], v[50:53], off
	s_cbranch_vccnz .LBB0_393
	v_and_b32_e32 v49, 64, v218
	v_xor_b32_e32 v48, 16, v218
	v_add_u32_e32 v49, 64, v49
	v_cmp_lt_i32_e32 vcc, v48, v49
	s_nop 1
	v_cndmask_b32_e32 v48, v218, v48, vcc
	v_lshlrev_b32_e32 v71, 2, v48
	ds_bpermute_b32 v48, v71, v42
	ds_bpermute_b32 v49, v71, v43
	ds_bpermute_b32 v50, v71, v38
	ds_bpermute_b32 v52, v71, v44
	ds_bpermute_b32 v53, v71, v45
	ds_bpermute_b32 v51, v71, v39
	ds_bpermute_b32 v70, v71, v40
	ds_bpermute_b32 v71, v71, v41
	s_waitcnt lgkmcnt(6)
	v_mul_f32_e32 v48, v66, v48
	v_mul_f32_e32 v49, v67, v49
	s_waitcnt lgkmcnt(3)
	v_mul_f32_e32 v52, v68, v52
	v_mul_f32_e32 v53, v69, v53
	v_mul_f32_e32 v48, v156, v48
	v_mul_f32_e32 v49, v157, v49
	s_waitcnt lgkmcnt(2)
	v_mul_f32_e32 v50, v62, v50
	v_mul_f32_e32 v51, v63, v51
	v_fma_f32 v42, v42, v58, v48
	v_fma_f32 v43, v43, v59, v49
	s_waitcnt lgkmcnt(0)
	v_mul_f32_e32 v48, v64, v70
	v_mul_f32_e32 v49, v65, v71
	v_mul_f32_e32 v52, v158, v52
	v_mul_f32_e32 v53, v159, v53
	v_mul_f32_e32 v50, v156, v50
	v_mul_f32_e32 v51, v157, v51
	v_mul_f32_e32 v48, v158, v48
	v_mul_f32_e32 v49, v159, v49
	v_fma_f32 v44, v44, v60, v52
	v_fma_f32 v45, v45, v61, v53
	v_fma_f32 v40, v40, v56, v48
	v_fma_f32 v41, v41, v57, v49
	v_fma_f32 v38, v38, v54, v50
	v_fma_f32 v39, v39, v55, v51
.LBB0_393:
	s_and_b64 vcc, exec, s[48:49]
	s_cbranch_vccnz .LBB0_395
	v_mul_f32_e32 v49, 0xbfb8aa3b, v38
	v_exp_f32_e32 v49, v49
	v_mul_f32_e32 v48, 0xbfb8aa3b, v42
	v_exp_f32_e32 v48, v48
	v_mul_f32_e32 v53, 0xbfb8aa3b, v40
	v_add_f32_e32 v49, 1.0, v49
	v_rcp_f32_e32 v50, v49
	v_mul_f32_e32 v49, 0xbfb8aa3b, v43
	v_exp_f32_e32 v49, v49
	v_add_f32_e32 v48, 1.0, v48
	v_exp_f32_e32 v53, v53
	v_rcp_f32_e32 v48, v48
	v_add_f32_e32 v49, 1.0, v49
	v_rcp_f32_e32 v49, v49
	v_add_f32_e32 v53, 1.0, v53
	v_mul_f32_e32 v51, 0xbfb8aa3b, v39
	v_mul_f32_e32 v52, 0xbfb8aa3b, v44
	v_rcp_f32_e32 v54, v53
	v_mul_f32_e32 v53, 0xbfb8aa3b, v45
	v_mul_f32_e32 v42, v42, v48
	v_mul_f32_e32 v43, v43, v49
	v_mul_f32_e32 v48, 0xbfb8aa3b, v41
	v_exp_f32_e32 v51, v51
	v_exp_f32_e32 v52, v52
	v_exp_f32_e32 v53, v53
	v_exp_f32_e32 v48, v48
	v_add_f32_e32 v51, 1.0, v51
	v_add_f32_e32 v52, 1.0, v52
	v_add_f32_e32 v53, 1.0, v53
	v_add_f32_e32 v48, 1.0, v48
	v_rcp_f32_e32 v51, v51
	v_rcp_f32_e32 v52, v52
	v_rcp_f32_e32 v53, v53
	v_rcp_f32_e32 v55, v48
	v_mul_f32_e32 v38, v38, v50
	v_mul_f32_e32 v39, v39, v51
	v_mul_f32_e32 v44, v44, v52
	v_mul_f32_e32 v45, v45, v53
	v_mul_f32_e32 v40, v40, v54
	v_mul_f32_e32 v41, v41, v55

; __device__ __forceinline__ unsigned pk2(float lo, float hi) { f32x2v v = {lo, hi}; bf16x2_t b = __builtin_convertvector(v, bf16x2_t); return __builtin_bit_cast(unsigned, b); }
;     __device__ __forceinline__ void operator()(const pg8::f32x4 (&acc)[2][2][4][2], const pg8::Unit& u, int wr, int wc, int fr, int fq) const {
;     ...
;                 const int row = row0 + ai * 128 + m * 16;
;                 const int tok = row & (SEQ - 1);
;                 bf16_t* rowp = base + (size_t)((row >> 13) * LP + PADF + NMETA + tok) * ldc + col0;
;                 const float scr = sc * rstd[row];
;                 f32x4 c0 = {1.f, 1.f, 1.f, 1.f}, c1 = c0, s0 = {0.f, 0.f, 0.f, 0.f}, s1 = s0;
;                 if (dorope) {
;                     const int pos = NMETA + tok;
;                     if (fq < 2) { c0 = *(const f32x4*)(ropec + pos * 8); c1 = *(const f32x4*)(ropec + pos * 8 + 4); s0 = *(const f32x4*)(ropes + pos * 8); s1 = *(const f32x4*)(ropes + pos * 8 + 4); }
;                 }
; #pragma unroll
;                 for (int bj = 0; bj < 2; ++bj) {
;                     f32x4 v0 = acc[ai][bj][m][0] * scr, v1 = acc[ai][bj][m][1] * scr;
;                     if (dorope) {
;                         f32x4 p0, p1;
; #pragma unroll
;                         for (int e = 0; e < 4; ++e) { p0[e] = __shfl_xor(v0[e], 16); p1[e] = __shfl_xor(v1[e], 16); }
;                         v0 = v0 * c0 + (p0 * s0) * sgn; v1 = v1 * c1 + (p1 * s1) * sgn;
;                     }
;                     if (silu) {
; #pragma unroll
;                         for (int e = 0; e < 4; ++e) { v0[e] = v0[e] * __builtin_amdgcn_rcpf(1.f + __builtin_amdgcn_exp2f(-LOG2E * v0[e])); v1[e] = v1[e] * __builtin_amdgcn_rcpf(1.f + __builtin_amdgcn_exp2f(-LOG2E * v1[e])); }
;                     }
;                     u32x4 w; w.x = pk2(v0[0], v0[1]); w.y = pk2(v0[2], v0[3]); w.z = pk2(v1[0], v1[1]); w.w = pk2(v1[2], v1[3]);
;                     *(u32x4*)(rowp + bj * 128) = w;
.LBB0_397:
	s_or_b64 exec, exec, s[20:21]
	v_mul_f32_e32 v54, s19, v54
	v_mul_f32_e32 v36, v36, v54
	v_mul_f32_e32 v37, v37, v54
	v_mul_f32_e32 v34, v34, v54
	v_mul_f32_e32 v35, v35, v54
	v_mul_f32_e32 v32, v32, v54
	v_mul_f32_e32 v33, v33, v54
	s_and_b64 vcc, exec, s[46:47]
	v_mul_f32_e32 v56, v30, v54
	v_mul_f32_e32 v57, v31, v54
	s_cbranch_vccnz .LBB0_399
	v_and_b32_e32 v31, 64, v218
	v_xor_b32_e32 v30, 16, v218
	v_add_u32_e32 v31, 64, v31
	v_cmp_lt_i32_e32 vcc, v30, v31
	s_nop 1
	v_cndmask_b32_e32 v30, v218, v30, vcc
	v_lshlrev_b32_e32 v55, 2, v30
	ds_bpermute_b32 v30, v55, v34
	ds_bpermute_b32 v31, v55, v35
	ds_bpermute_b32 v60, v55, v56
	ds_bpermute_b32 v62, v55, v36
	ds_bpermute_b32 v63, v55, v37
	ds_bpermute_b32 v61, v55, v57
	ds_bpermute_b32 v64, v55, v32
	ds_bpermute_b32 v65, v55, v33
	s_waitcnt lgkmcnt(6)
	v_mul_f32_e32 v30, v50, v30
	v_mul_f32_e32 v31, v51, v31
	s_waitcnt lgkmcnt(3)
	v_mul_f32_e32 v62, v52, v62
	v_mul_f32_e32 v63, v53, v63
	v_mul_f32_e32 v30, v156, v30
	v_mul_f32_e32 v31, v157, v31
	s_waitcnt lgkmcnt(2)
	v_mul_f32_e32 v60, v46, v60
	v_mul_f32_e32 v61, v47, v61
	v_fma_f32 v34, v34, v42, v30
	v_fma_f32 v35, v35, v43, v31
	s_waitcnt lgkmcnt(0)
	v_mul_f32_e32 v30, v48, v64
	v_mul_f32_e32 v31, v49, v65
	v_mul_f32_e32 v62, v158, v62
	v_mul_f32_e32 v63, v159, v63
	v_mul_f32_e32 v60, v156, v60
	v_mul_f32_e32 v61, v157, v61
	v_mul_f32_e32 v30, v158, v30
	v_mul_f32_e32 v31, v159, v31
	v_fma_f32 v36, v36, v44, v62
	v_fma_f32 v37, v37, v45, v63
	v_fma_f32 v32, v32, v40, v30
	v_fma_f32 v33, v33, v41, v31
	v_fma_f32 v56, v56, v38, v60
	v_fma_f32 v57, v57, v39, v61
.LBB0_399:
	s_and_b64 vcc, exec, s[48:49]
	s_cbranch_vccnz .LBB0_401
	v_mul_f32_e32 v55, 0xbfb8aa3b, v57
	v_exp_f32_e32 v55, v55
	v_mul_f32_e32 v31, 0xbfb8aa3b, v56
	v_exp_f32_e32 v31, v31
	v_mul_f32_e32 v30, 0xbfb8aa3b, v34
	v_add_f32_e32 v55, 1.0, v55
	v_rcp_f32_e32 v61, v55
	v_mul_f32_e32 v55, 0xbfb8aa3b, v36
	v_add_f32_e32 v31, 1.0, v31
	v_exp_f32_e32 v55, v55
	v_rcp_f32_e32 v60, v31
	v_mul_f32_e32 v31, 0xbfb8aa3b, v35
	v_exp_f32_e32 v30, v30
	v_exp_f32_e32 v31, v31
	v_add_f32_e32 v55, 1.0, v55
	v_rcp_f32_e32 v62, v55
	v_mul_f32_e32 v55, 0xbfb8aa3b, v32
	v_add_f32_e32 v30, 1.0, v30
	v_add_f32_e32 v31, 1.0, v31
	v_exp_f32_e32 v55, v55
	v_rcp_f32_e32 v30, v30
	v_rcp_f32_e32 v31, v31
	v_mul_f32_e32 v56, v56, v60
	v_mul_f32_e32 v57, v57, v61
	v_add_f32_e32 v55, 1.0, v55
	v_rcp_f32_e32 v64, v55
	v_mul_f32_e32 v55, 0xbfb8aa3b, v37
	v_mul_f32_e32 v34, v34, v30
	v_mul_f32_e32 v35, v35, v31
	v_mul_f32_e32 v30, 0xbfb8aa3b, v33
	v_exp_f32_e32 v55, v55
	v_exp_f32_e32 v30, v30
	v_add_f32_e32 v55, 1.0, v55
	v_add_f32_e32 v30, 1.0, v30
	v_rcp_f32_e32 v63, v55
	v_rcp_f32_e32 v65, v30
	v_mul_f32_e32 v36, v36, v62
	v_mul_f32_e32 v37, v37, v63
	v_mul_f32_e32 v32, v32, v64
	v_mul_f32_e32 v33, v33, v65
.LBB0_401:
	v_add_u32_e32 v30, v86, v58
	v_ashrrev_i32_e32 v31, 31, v30
	v_mul_lo_u32 v58, s2, v31
	v_mul_lo_u32 v59, s3, v30
	v_mad_u64_u32 v[30:31], s[0:1], s2, v30, 0
	v_mov_b32_e32 v55, v54
	v_add3_u32 v31, v31, v58, v59
	v_cvt_pk_bf16_f32 v34, v34, v35
	v_cvt_pk_bf16_f32 v35, v36, v37
	v_cvt_pk_bf16_f32 v37, v32, v33
	v_mov_b32_e32 v32, v54
	v_mov_b32_e32 v33, v54
	v_lshl_add_u64 v[30:31], v[30:31], 1, v[168:169]
	v_cvt_pk_bf16_f32 v36, v56, v57
	v_mul_f32_e32 v28, v28, v32
	v_mul_f32_e32 v29, v29, v33
	v_mul_f32_e32 v26, v26, v54
	v_mul_f32_e32 v27, v27, v55
	v_mul_f32_e32 v24, v24, v32
	v_mul_f32_e32 v25, v25, v33
	s_and_b64 vcc, exec, s[46:47]
	v_mul_f32_e32 v22, v22, v54
	v_mul_f32_e32 v23, v23, v55
	global_store_dwordx4 v[30:31], v[34:37], off
	s_cbranch_vccnz .LBB0_403
	v_and_b32_e32 v33, 64, v218
	v_xor_b32_e32 v32, 16, v218
	v_add_u32_e32 v33, 64, v33
	v_cmp_lt_i32_e32 vcc, v32, v33
	s_nop 1
	v_cndmask_b32_e32 v32, v218, v32, vcc
	v_lshlrev_b32_e32 v55, 2, v32
	ds_bpermute_b32 v32, v55, v26
	ds_bpermute_b32 v33, v55, v27
	ds_bpermute_b32 v34, v55, v22
	ds_bpermute_b32 v36, v55, v28
	ds_bpermute_b32 v37, v55, v29
	ds_bpermute_b32 v35, v55, v23
	ds_bpermute_b32 v54, v55, v24
	ds_bpermute_b32 v55, v55, v25
	s_waitcnt lgkmcnt(6)
	v_mul_f32_e32 v32, v50, v32
	v_mul_f32_e32 v33, v51, v33
	s_waitcnt lgkmcnt(3)
	v_mul_f32_e32 v36, v52, v36
	v_mul_f32_e32 v37, v53, v37
	v_mul_f32_e32 v32, v156, v32
	v_mul_f32_e32 v33, v157, v33
	s_waitcnt lgkmcnt(2)
	v_mul_f32_e32 v34, v46, v34
	v_mul_f32_e32 v35, v47, v35
	v_fma_f32 v26, v26, v42, v32
	v_fma_f32 v27, v27, v43, v33
	s_waitcnt lgkmcnt(0)
	v_mul_f32_e32 v32, v48, v54
	v_mul_f32_e32 v33, v49, v55
	v_mul_f32_e32 v36, v158, v36
	v_mul_f32_e32 v37, v159, v37
	v_mul_f32_e32 v34, v156, v34
	v_mul_f32_e32 v35, v157, v35
	v_mul_f32_e32 v32, v158, v32
	v_mul_f32_e32 v33, v159, v33
	v_fma_f32 v28, v28, v44, v36
	v_fma_f32 v29, v29, v45, v37
	v_fma_f32 v24, v24, v40, v32
	v_fma_f32 v25, v25, v41, v33
	v_fma_f32 v22, v22, v38, v34
	v_fma_f32 v23, v23, v39, v35
.LBB0_403:
	s_and_b64 vcc, exec, s[48:49]
	s_cbranch_vccnz .LBB0_405
	v_mul_f32_e32 v33, 0xbfb8aa3b, v22
	v_exp_f32_e32 v33, v33
	v_mul_f32_e32 v32, 0xbfb8aa3b, v26
	v_exp_f32_e32 v32, v32
	v_mul_f32_e32 v37, 0xbfb8aa3b, v24
	v_add_f32_e32 v33, 1.0, v33
	v_rcp_f32_e32 v34, v33
	v_mul_f32_e32 v33, 0xbfb8aa3b, v27
	v_exp_f32_e32 v33, v33
	v_add_f32_e32 v32, 1.0, v32
	v_exp_f32_e32 v37, v37
	v_rcp_f32_e32 v32, v32
	v_add_f32_e32 v33, 1.0, v33
	v_rcp_f32_e32 v33, v33
	v_add_f32_e32 v37, 1.0, v37
	v_mul_f32_e32 v35, 0xbfb8aa3b, v23
	v_mul_f32_e32 v36, 0xbfb8aa3b, v28
	v_rcp_f32_e32 v38, v37
	v_mul_f32_e32 v37, 0xbfb8aa3b, v29
	v_mul_f32_e32 v26, v26, v32
	v_mul_f32_e32 v27, v27, v33
	v_mul_f32_e32 v32, 0xbfb8aa3b, v25
	v_exp_f32_e32 v35, v35
	v_exp_f32_e32 v36, v36
	v_exp_f32_e32 v37, v37
	v_exp_f32_e32 v32, v32
	v_add_f32_e32 v35, 1.0, v35
	v_add_f32_e32 v36, 1.0, v36
	v_add_f32_e32 v37, 1.0, v37
	v_add_f32_e32 v32, 1.0, v32
	v_rcp_f32_e32 v35, v35
	v_rcp_f32_e32 v36, v36
	v_rcp_f32_e32 v37, v37
	v_rcp_f32_e32 v39, v32
	v_mul_f32_e32 v22, v22, v34
	v_mul_f32_e32 v23, v23, v35
	v_mul_f32_e32 v28, v28, v36
	v_mul_f32_e32 v29, v29, v37
	v_mul_f32_e32 v24, v24, v38
	v_mul_f32_e32 v25, v25, v39

; __device__ __forceinline__ unsigned pk2(float lo, float hi) { f32x2v v = {lo, hi}; bf16x2_t b = __builtin_convertvector(v, bf16x2_t); return __builtin_bit_cast(unsigned, b); }
;     __device__ __forceinline__ void operator()(const pg8::f32x4 (&acc)[2][2][4][2], const pg8::Unit& u, int wr, int wc, int fr, int fq) const {
;     ...
;                 const int row = row0 + ai * 128 + m * 16;
;                 const int tok = row & (SEQ - 1);
;                 bf16_t* rowp = base + (size_t)((row >> 13) * LP + PADF + NMETA + tok) * ldc + col0;
;                 const float scr = sc * rstd[row];
;                 f32x4 c0 = {1.f, 1.f, 1.f, 1.f}, c1 = c0, s0 = {0.f, 0.f, 0.f, 0.f}, s1 = s0;
;                 if (dorope) {
;                     const int pos = NMETA + tok;
;                     if (fq < 2) { c0 = *(const f32x4*)(ropec + pos * 8); c1 = *(const f32x4*)(ropec + pos * 8 + 4); s0 = *(const f32x4*)(ropes + pos * 8); s1 = *(const f32x4*)(ropes + pos * 8 + 4); }
;                 }
; #pragma unroll
;                 for (int bj = 0; bj < 2; ++bj) {
;                     f32x4 v0 = acc[ai][bj][m][0] * scr, v1 = acc[ai][bj][m][1] * scr;
;                     if (dorope) {
;                         f32x4 p0, p1;
; #pragma unroll
;                         for (int e = 0; e < 4; ++e) { p0[e] = __shfl_xor(v0[e], 16); p1[e] = __shfl_xor(v1[e], 16); }
;                         v0 = v0 * c0 + (p0 * s0) * sgn; v1 = v1 * c1 + (p1 * s1) * sgn;
;                     }
;                     if (silu) {
; #pragma unroll
;                         for (int e = 0; e < 4; ++e) { v0[e] = v0[e] * __builtin_amdgcn_rcpf(1.f + __builtin_amdgcn_exp2f(-LOG2E * v0[e])); v1[e] = v1[e] * __builtin_amdgcn_rcpf(1.f + __builtin_amdgcn_exp2f(-LOG2E * v1[e])); }
;                     }
;                     u32x4 w; w.x = pk2(v0[0], v0[1]); w.y = pk2(v0[2], v0[3]); w.z = pk2(v1[0], v1[1]); w.w = pk2(v1[2], v1[3]);
;                     *(u32x4*)(rowp + bj * 128) = w;
.LBB0_407:
	s_or_b64 exec, exec, s[20:21]
	v_mul_f32_e32 v38, s19, v38
	v_mul_f32_e32 v20, v20, v38
	v_mul_f32_e32 v21, v21, v38
	v_mul_f32_e32 v18, v18, v38
	v_mul_f32_e32 v19, v19, v38
	v_mul_f32_e32 v12, v12, v38
	v_mul_f32_e32 v13, v13, v38
	s_and_b64 vcc, exec, s[46:47]
	v_mul_f32_e32 v40, v10, v38
	v_mul_f32_e32 v41, v11, v38
	s_mov_b32 s31, 0xbfb8aa3b
	s_cbranch_vccnz .LBB0_409
	v_and_b32_e32 v11, 64, v218
	v_xor_b32_e32 v10, 16, v218
	v_add_u32_e32 v11, 64, v11
	v_cmp_lt_i32_e32 vcc, v10, v11
	s_nop 1
	v_cndmask_b32_e32 v10, v218, v10, vcc
	v_lshlrev_b32_e32 v39, 2, v10
	ds_bpermute_b32 v10, v39, v18
	ds_bpermute_b32 v11, v39, v19
	ds_bpermute_b32 v44, v39, v40
	ds_bpermute_b32 v46, v39, v20
	ds_bpermute_b32 v47, v39, v21
	ds_bpermute_b32 v45, v39, v41
	ds_bpermute_b32 v48, v39, v12
	ds_bpermute_b32 v49, v39, v13
	s_waitcnt lgkmcnt(6)
	v_mul_f32_e32 v10, v34, v10
	v_mul_f32_e32 v11, v35, v11
	s_waitcnt lgkmcnt(3)
	v_mul_f32_e32 v46, v36, v46
	v_mul_f32_e32 v47, v37, v47
	v_mul_f32_e32 v10, v156, v10
	v_mul_f32_e32 v11, v157, v11
	s_waitcnt lgkmcnt(2)
	v_mul_f32_e32 v44, v30, v44
	v_mul_f32_e32 v45, v31, v45
	v_fma_f32 v18, v18, v26, v10
	v_fma_f32 v19, v19, v27, v11
	s_waitcnt lgkmcnt(0)
	v_mul_f32_e32 v10, v32, v48
	v_mul_f32_e32 v11, v33, v49
	v_mul_f32_e32 v46, v158, v46
	v_mul_f32_e32 v47, v159, v47
	v_mul_f32_e32 v44, v156, v44
	v_mul_f32_e32 v45, v157, v45
	v_mul_f32_e32 v10, v158, v10
	v_mul_f32_e32 v11, v159, v11
	v_fma_f32 v20, v20, v28, v46
	v_fma_f32 v21, v21, v29, v47
	v_fma_f32 v12, v12, v24, v10
	v_fma_f32 v13, v13, v25, v11
	v_fma_f32 v40, v40, v22, v44
	v_fma_f32 v41, v41, v23, v45
.LBB0_409:
	s_and_b64 vcc, exec, s[48:49]
	s_cbranch_vccnz .LBB0_411
	v_mul_f32_e32 v39, 0xbfb8aa3b, v41
	v_exp_f32_e32 v39, v39
	v_mul_f32_e32 v11, 0xbfb8aa3b, v40
	v_exp_f32_e32 v11, v11
	v_mul_f32_e32 v10, 0xbfb8aa3b, v18
	v_add_f32_e32 v39, 1.0, v39
	v_rcp_f32_e32 v45, v39
	v_mul_f32_e32 v39, 0xbfb8aa3b, v20
	v_add_f32_e32 v11, 1.0, v11
	v_exp_f32_e32 v39, v39
	v_rcp_f32_e32 v44, v11
	v_mul_f32_e32 v11, 0xbfb8aa3b, v19
	v_exp_f32_e32 v10, v10
	v_exp_f32_e32 v11, v11
	v_add_f32_e32 v39, 1.0, v39
	v_rcp_f32_e32 v46, v39
	v_mul_f32_e32 v39, 0xbfb8aa3b, v12
	v_add_f32_e32 v10, 1.0, v10
	v_add_f32_e32 v11, 1.0, v11
	v_exp_f32_e32 v39, v39
	v_rcp_f32_e32 v10, v10
	v_rcp_f32_e32 v11, v11
	v_mul_f32_e32 v40, v40, v44
	v_mul_f32_e32 v41, v41, v45
	v_add_f32_e32 v39, 1.0, v39
	v_rcp_f32_e32 v48, v39
	v_mul_f32_e32 v39, 0xbfb8aa3b, v21
	v_mul_f32_e32 v18, v18, v10
	v_mul_f32_e32 v19, v19, v11
	v_mul_f32_e32 v10, 0xbfb8aa3b, v13
	v_exp_f32_e32 v39, v39
	v_exp_f32_e32 v10, v10
	v_add_f32_e32 v39, 1.0, v39
	v_add_f32_e32 v10, 1.0, v10
	v_rcp_f32_e32 v47, v39
	v_rcp_f32_e32 v49, v10
	v_mul_f32_e32 v20, v20, v46
	v_mul_f32_e32 v21, v21, v47
	v_mul_f32_e32 v12, v12, v48
	v_mul_f32_e32 v13, v13, v49
.LBB0_411:
	v_add_u32_e32 v10, v86, v42
	v_ashrrev_i32_e32 v11, 31, v10
	v_mul_lo_u32 v42, s2, v11
	v_mul_lo_u32 v43, s3, v10
	v_mad_u64_u32 v[10:11], s[0:1], s2, v10, 0
	v_mov_b32_e32 v39, v38
	v_add3_u32 v11, v11, v42, v43
	v_cvt_pk_bf16_f32 v18, v18, v19
	v_cvt_pk_bf16_f32 v19, v20, v21
	v_cvt_pk_bf16_f32 v21, v12, v13
	v_mov_b32_e32 v12, v38
	v_mov_b32_e32 v13, v38
	v_lshl_add_u64 v[10:11], v[10:11], 1, v[168:169]
	v_cvt_pk_bf16_f32 v20, v40, v41
	v_mul_f32_e32 v8, v8, v12
	v_mul_f32_e32 v9, v9, v13
	v_mul_f32_e32 v6, v6, v38
	v_mul_f32_e32 v7, v7, v39
	v_mul_f32_e32 v4, v4, v12
	v_mul_f32_e32 v5, v5, v13
	s_and_b64 vcc, exec, s[46:47]
	v_mul_f32_e32 v2, v2, v38
	v_mul_f32_e32 v3, v3, v39
	global_store_dwordx4 v[10:11], v[18:21], off
	s_cbranch_vccnz .LBB0_413
	v_and_b32_e32 v13, 64, v218
	v_xor_b32_e32 v12, 16, v218
	v_add_u32_e32 v13, 64, v13
	v_cmp_lt_i32_e32 vcc, v12, v13
	s_nop 1
	v_cndmask_b32_e32 v12, v218, v12, vcc
	v_lshlrev_b32_e32 v39, 2, v12
	ds_bpermute_b32 v12, v39, v6
	ds_bpermute_b32 v13, v39, v7
	ds_bpermute_b32 v18, v39, v2
	ds_bpermute_b32 v20, v39, v8
	ds_bpermute_b32 v21, v39, v9
	ds_bpermute_b32 v19, v39, v3
	ds_bpermute_b32 v38, v39, v4
	ds_bpermute_b32 v39, v39, v5
	s_waitcnt lgkmcnt(6)
	v_mul_f32_e32 v12, v34, v12
	v_mul_f32_e32 v13, v35, v13
	s_waitcnt lgkmcnt(3)
	v_mul_f32_e32 v20, v36, v20
	v_mul_f32_e32 v21, v37, v21
	v_mul_f32_e32 v12, v156, v12
	v_mul_f32_e32 v13, v157, v13
	s_waitcnt lgkmcnt(2)
	v_mul_f32_e32 v18, v30, v18
	v_mul_f32_e32 v19, v31, v19
	v_fma_f32 v6, v6, v26, v12
	v_fma_f32 v7, v7, v27, v13
	s_waitcnt lgkmcnt(0)
	v_mul_f32_e32 v12, v32, v38
	v_mul_f32_e32 v13, v33, v39
	v_mul_f32_e32 v20, v158, v20
	v_mul_f32_e32 v21, v159, v21
	v_mul_f32_e32 v18, v156, v18
	v_mul_f32_e32 v19, v157, v19
	v_mul_f32_e32 v12, v158, v12
	v_mul_f32_e32 v13, v159, v13
	v_fma_f32 v8, v8, v28, v20
	v_fma_f32 v9, v9, v29, v21
	v_fma_f32 v4, v4, v24, v12
	v_fma_f32 v5, v5, v25, v13
	v_fma_f32 v2, v2, v22, v18
	v_fma_f32 v3, v3, v23, v19
.LBB0_413:
	s_and_b64 vcc, exec, s[48:49]
	s_cbranch_vccnz .LBB0_415
	v_mul_f32_e32 v13, 0xbfb8aa3b, v2
	v_exp_f32_e32 v13, v13
	v_mul_f32_e32 v12, 0xbfb8aa3b, v6
	v_exp_f32_e32 v12, v12
	v_mul_f32_e32 v21, 0xbfb8aa3b, v4
	v_add_f32_e32 v13, 1.0, v13
	v_rcp_f32_e32 v18, v13
	v_mul_f32_e32 v13, 0xbfb8aa3b, v7
	v_exp_f32_e32 v13, v13
	v_add_f32_e32 v12, 1.0, v12
	v_exp_f32_e32 v21, v21
	v_rcp_f32_e32 v12, v12
	v_add_f32_e32 v13, 1.0, v13
	v_rcp_f32_e32 v13, v13
	v_add_f32_e32 v21, 1.0, v21
	v_mul_f32_e32 v19, 0xbfb8aa3b, v3
	v_mul_f32_e32 v20, 0xbfb8aa3b, v8
	v_rcp_f32_e32 v22, v21
	v_mul_f32_e32 v21, 0xbfb8aa3b, v9
	v_mul_f32_e32 v6, v6, v12
	v_mul_f32_e32 v7, v7, v13
	v_mul_f32_e32 v12, 0xbfb8aa3b, v5
	v_exp_f32_e32 v19, v19
	v_exp_f32_e32 v20, v20
	v_exp_f32_e32 v21, v21
	v_exp_f32_e32 v12, v12
	v_add_f32_e32 v19, 1.0, v19
	v_add_f32_e32 v20, 1.0, v20
	v_add_f32_e32 v21, 1.0, v21
	v_add_f32_e32 v12, 1.0, v12
	v_rcp_f32_e32 v19, v19
	v_rcp_f32_e32 v20, v20
	v_rcp_f32_e32 v21, v21
	v_rcp_f32_e32 v23, v12
	v_mul_f32_e32 v2, v2, v18
	v_mul_f32_e32 v3, v3, v19
	v_mul_f32_e32 v8, v8, v20
	v_mul_f32_e32 v9, v9, v21
	v_mul_f32_e32 v4, v4, v22
	v_mul_f32_e32 v5, v5, v23
